# attention loops: lgkmcnt waits batched (one wait per four K/V fragments)
# speedup vs baseline: 1.1072x; 1.0023x over previous
;   DI void qk(int buf, f32x16 (&s)[2]) {
;     ...
;     for (int ks = 0; ks < NKS; ++ks)
; #pragma unroll
;       for (int kb2 = 0; kb2 < 2; ++kb2) {
;         const bf16x8 a = *(const bf16x8*)(kb + kb2 * 32 * KP + ks * 16);
;         s[kb2] = MFMA(a, qf[ks], s[kb2]);
;       }
;     s[0] = MFMA(kone, qm, s[0]);
;     s[1] = MFMA(kone, qm, s[1]);
;   template <int PAR>
;   DI void step(int t, f32x16 (&cur)[2], f32x16 (&nxt)[2]) {
;     if (t + 1 < nt) sstore_k(PAR ^ 1);
;     if (t > 0) sstore_v(PAR);
;     __syncthreads();
;     if (t + 1 < nt) qk(PAR ^ 1, nxt);
;     float mx = fmaxf(cur[0][0], cur[1][0]);
; #pragma unroll
;     for (int i = 1; i < 16; ++i) mx = fmaxf(fmaxf(cur[0][i], cur[1][i]), mx);
;     if (__builtin_amdgcn_ballot_w64(mx > ATT_THR) != 0ull) {
;       asm volatile("" ::: "memory");
;       mx = fmaxf(mx, xhalf(mx));
;       const float want = mref + fmaxf(mx, 0.f);
;       const float mn = __uint_as_float(pack2(want, 0.f) << 16);
;       const float d = mn - mref;
;       const float alpha = __builtin_amdgcn_exp2f(-d);
;       mref = mn;
;       l *= alpha;
; #pragma unroll
;       for (int a = 0; a < 2; ++a)
; #pragma unroll
;         for (int i = 0; i < 16; ++i) { o[a][i] *= alpha; cur[a][i] -= d; nxt[a][i] -= d; }
;       u32x4 q4 = {h == 0 ? (pack2(-mn, 0.f) & 0xffffu) : 0u, 0u, 0u, 0u};
;       qm = __builtin_bit_cast(bf16x8, q4);
;     }
;     float psum = 0.f;
; #pragma unroll
;     for (int kb2 = 0; kb2 < 2; ++kb2)
; #pragma unroll
;       for (int i = 0; i < 16; ++i) { const float pv = __builtin_amdgcn_exp2f(cur[kb2][i]); cur[kb2][i] = pv; psum += pv; }
;     l += psum;
;     if (t + 2 < nt) gload_k(t + 2);
;     if (t + 1 < nt) gload_v(t + 1);
;     const u16* vb = sV + PAR * VBUF + r * GP + h * 8;
; #pragma unroll
;     for (int kb2 = 0; kb2 < 2; ++kb2)
; #pragma unroll
;       for (int s2 = 0; s2 < 2; ++s2) {
;         u32x4 pk = {pack2(cur[kb2][8 * s2], cur[kb2][8 * s2 + 1]), pack2(cur[kb2][8 * s2 + 2], cur[kb2][8 * s2 + 3]),
;                     pack2(cur[kb2][8 * s2 + 4], cur[kb2][8 * s2 + 5]), pack2(cur[kb2][8 * s2 + 6], cur[kb2][8 * s2 + 7])};
;         const bf16x8 pf = __builtin_bit_cast(bf16x8, pk);
; #pragma unroll
;         for (int db = 0; db < 2; ++db) {
;           const bf16x8 a = *(const bf16x8*)(vb + db * 32 * GP + kb2 * 32 + s2 * 16);
;           o[db] = MFMA(a, pf, o[db]);
;         }
;       }
;   }
.Lgf_rareA_ret:
	v_exp_f32_e32 v48, v48
	v_exp_f32_e32 v49, v49
	v_exp_f32_e32 v50, v50
	v_add_f32_e32 v182, v48, v182
	v_exp_f32_e32 v51, v51
	v_add_f32_e32 v183, v49, v183
	v_exp_f32_e32 v52, v52
	v_add_f32_e32 v182, v50, v182
	s_waitcnt lgkmcnt(4)
	v_mfma_f32_32x32x16_bf16 v[80:95], v[96:99], v[136:139], 0
	v_exp_f32_e32 v53, v53
	v_add_f32_e32 v183, v51, v183
	v_exp_f32_e32 v54, v54
	v_add_f32_e32 v182, v52, v182
	v_exp_f32_e32 v55, v55
	v_add_f32_e32 v183, v53, v183
	v_mfma_f32_32x32x16_bf16 v[64:79], v[100:103], v[136:139], 0
	v_cvt_pk_bf16_f32 v48, v48, v49
	v_add_f32_e32 v182, v54, v182
	v_cvt_pk_bf16_f32 v49, v50, v51
	v_add_f32_e32 v183, v55, v183
	v_cvt_pk_bf16_f32 v50, v52, v53
	v_cvt_pk_bf16_f32 v51, v54, v55
	v_mfma_f32_32x32x16_bf16 v[80:95], v[104:107], v[140:143], v[80:95]
	v_exp_f32_e32 v56, v56
	v_exp_f32_e32 v57, v57
	v_exp_f32_e32 v58, v58
	v_add_f32_e32 v182, v56, v182
	v_exp_f32_e32 v59, v59
	v_add_f32_e32 v183, v57, v183
	v_mfma_f32_32x32x16_bf16 v[64:79], v[108:111], v[140:143], v[64:79]
	v_exp_f32_e32 v60, v60
	v_add_f32_e32 v182, v58, v182
	v_exp_f32_e32 v61, v61
	v_add_f32_e32 v183, v59, v183
	v_exp_f32_e32 v62, v62
	v_add_f32_e32 v182, v60, v182
	s_waitcnt vmcnt(0)
	s_waitcnt lgkmcnt(0)
	s_barrier
	s_add_i32 s0, s45, -1
	s_cmp_ge_u32 s0, s19
	s_cselect_b64 s[14:15], -1, 0
	s_cmp_ge_u32 s45, s19
	s_cbranch_scc1 .Lgf_skipKA
	s_add_i32 m0, s46, 9216
	s_nop 0
	global_load_lds_dwordx4 v[214:215], off
	global_load_lds_dwordx4 v[216:217], off offset:1024
	v_lshl_add_u64 v[214:215], v[214:215], 0, s[20:21]
	v_lshl_add_u64 v[216:217], v[216:217], 0, s[20:21]
.Lgf_skipKA:
	s_add_i32 m0, s46, 27648
	s_nop 0
	global_load_lds_dwordx4 v[160:161], off
	global_load_lds_dwordx4 v[162:163], off offset:1024
	v_lshl_add_u64 v[160:161], v[160:161], 0, s[84:85]
	v_lshl_add_u64 v[162:163], v[162:163], 0, s[84:85]
	ds_read_b128 v[96:99], v156 offset:18432
	ds_read_b128 v[100:103], v156 offset:22528
	ds_read_b128 v[104:107], v157 offset:18432
	ds_read_b128 v[108:111], v157 offset:22528
	v_mfma_f32_32x32x16_bf16 v[80:95], v[112:115], v[144:147], v[80:95]
	ds_read_b128 v[112:115], v158 offset:18432
	v_exp_f32_e32 v63, v63
	v_add_f32_e32 v183, v61, v183
	v_cvt_pk_bf16_f32 v56, v56, v57
	v_add_f32_e32 v182, v62, v182
	v_cvt_pk_bf16_f32 v57, v58, v59
	v_add_f32_e32 v183, v63, v183
	v_mfma_f32_32x32x16_bf16 v[64:79], v[116:119], v[144:147], v[64:79]
	ds_read_b128 v[116:119], v158 offset:22528
	v_cvt_pk_bf16_f32 v58, v60, v61
	v_cvt_pk_bf16_f32 v59, v62, v63
	v_exp_f32_e32 v32, v32
	v_exp_f32_e32 v33, v33
	v_exp_f32_e32 v34, v34
	v_add_f32_e32 v182, v32, v182
	v_mfma_f32_32x32x16_bf16 v[80:95], v[120:123], v[148:151], v[80:95]
	ds_read_b128 v[120:123], v159 offset:18432
	v_exp_f32_e32 v35, v35
	v_add_f32_e32 v183, v33, v183
	v_exp_f32_e32 v36, v36
	v_add_f32_e32 v182, v34, v182
	v_exp_f32_e32 v37, v37
	v_add_f32_e32 v183, v35, v183
	v_mfma_f32_32x32x16_bf16 v[64:79], v[124:127], v[148:151], v[64:79]
	ds_read_b128 v[124:127], v159 offset:22528
	v_exp_f32_e32 v38, v38
	v_add_f32_e32 v182, v36, v182
	v_exp_f32_e32 v39, v39
	v_add_f32_e32 v183, v37, v183
	v_cvt_pk_bf16_f32 v32, v32, v33
	v_add_f32_e32 v182, v38, v182
	s_waitcnt lgkmcnt(4)
	v_mfma_f32_32x32x16_bf16 v[16:31], v[96:99], v[48:51], v[16:31]
	ds_read_b128 v[96:99], v152
	v_cvt_pk_bf16_f32 v33, v34, v35
	v_add_f32_e32 v183, v39, v183
	v_cvt_pk_bf16_f32 v34, v36, v37
	v_cvt_pk_bf16_f32 v35, v38, v39
	v_exp_f32_e32 v40, v40
	v_mfma_f32_32x32x16_bf16 v[0:15], v[100:103], v[48:51], v[0:15]
	ds_read_b128 v[100:103], v152 offset:4096
	v_exp_f32_e32 v41, v41
	v_exp_f32_e32 v42, v42
	v_add_f32_e32 v182, v40, v182
	v_exp_f32_e32 v43, v43
	v_add_f32_e32 v183, v41, v183
	v_mfma_f32_32x32x16_bf16 v[16:31], v[104:107], v[56:59], v[16:31]
	ds_read_b128 v[104:107], v153
	v_exp_f32_e32 v44, v44
	v_add_f32_e32 v182, v42, v182
	v_exp_f32_e32 v45, v45
	v_add_f32_e32 v183, v43, v183
	v_exp_f32_e32 v46, v46
	v_mfma_f32_32x32x16_bf16 v[0:15], v[108:111], v[56:59], v[0:15]
	ds_read_b128 v[108:111], v153 offset:4096
	v_add_f32_e32 v182, v44, v182
	v_exp_f32_e32 v47, v47
	v_add_f32_e32 v183, v45, v183
	v_cvt_pk_bf16_f32 v40, v40, v41
	v_add_f32_e32 v182, v46, v182
	s_waitcnt lgkmcnt(4)
	v_mfma_f32_32x32x16_bf16 v[16:31], v[112:115], v[32:35], v[16:31]
	ds_read_b128 v[112:115], v154
	v_cvt_pk_bf16_f32 v41, v42, v43
	v_add_f32_e32 v183, v47, v183
	v_cvt_pk_bf16_f32 v42, v44, v45
	v_cvt_pk_bf16_f32 v43, v46, v47
	v_max3_f32 v128, v80, v64, v81
	v_mfma_f32_32x32x16_bf16 v[0:15], v[116:119], v[32:35], v[0:15]
	ds_read_b128 v[116:119], v154 offset:4096
	v_max3_f32 v172, v65, v82, v66
	v_max3_f32 v128, v83, v67, v128
	v_max3_f32 v172, v84, v68, v172
	v_max3_f32 v128, v85, v69, v128
	v_max3_f32 v172, v86, v70, v172
	v_mfma_f32_32x32x16_bf16 v[16:31], v[120:123], v[40:43], v[16:31]
	ds_read_b128 v[120:123], v155
	v_max3_f32 v128, v87, v71, v128
	v_max3_f32 v172, v88, v72, v172
	v_max3_f32 v128, v89, v73, v128
	v_max3_f32 v172, v90, v74, v172
	v_max3_f32 v128, v91, v75, v128
	v_mfma_f32_32x32x16_bf16 v[0:15], v[124:127], v[40:43], v[0:15]
	ds_read_b128 v[124:127], v155 offset:4096
	v_max3_f32 v172, v92, v76, v172
	v_max3_f32 v128, v93, v77, v128
	v_max3_f32 v172, v94, v78, v172
	v_max3_f32 v128, v95, v79, v128
	v_max_f32_e32 v128, v128, v172
	v_cmp_lt_f32_e32 vcc, s65, v128
	s_cbranch_vccnz .Lgf_rareB
.Lgf_rareB_ret:
	v_exp_f32_e32 v80, v80
	v_exp_f32_e32 v81, v81
	v_exp_f32_e32 v82, v82
	v_add_f32_e32 v182, v80, v182
	v_exp_f32_e32 v83, v83
	v_add_f32_e32 v183, v81, v183
	v_exp_f32_e32 v84, v84
	v_add_f32_e32 v182, v82, v182
	s_waitcnt lgkmcnt(4)
	v_mfma_f32_32x32x16_bf16 v[48:63], v[96:99], v[136:139], 0
	v_exp_f32_e32 v85, v85
	v_add_f32_e32 v183, v83, v183
	v_exp_f32_e32 v86, v86
	v_add_f32_e32 v182, v84, v182
	v_exp_f32_e32 v87, v87
	v_add_f32_e32 v183, v85, v183
	v_mfma_f32_32x32x16_bf16 v[32:47], v[100:103], v[136:139], 0
	v_cvt_pk_bf16_f32 v80, v80, v81
	v_add_f32_e32 v182, v86, v182
	v_cvt_pk_bf16_f32 v81, v82, v83
	v_add_f32_e32 v183, v87, v183
	v_cvt_pk_bf16_f32 v82, v84, v85
	v_cvt_pk_bf16_f32 v83, v86, v87
	v_mfma_f32_32x32x16_bf16 v[48:63], v[104:107], v[140:143], v[48:63]
	v_exp_f32_e32 v88, v88
	v_exp_f32_e32 v89, v89
	v_exp_f32_e32 v90, v90
	v_add_f32_e32 v182, v88, v182
	v_exp_f32_e32 v91, v91
	v_add_f32_e32 v183, v89, v183
	v_mfma_f32_32x32x16_bf16 v[32:47], v[108:111], v[140:143], v[32:47]
	v_exp_f32_e32 v92, v92
	v_add_f32_e32 v182, v90, v182
	v_exp_f32_e32 v93, v93
	v_add_f32_e32 v183, v91, v183
	v_exp_f32_e32 v94, v94
	v_add_f32_e32 v182, v92, v182
	s_waitcnt vmcnt(0)
	s_waitcnt lgkmcnt(0)
	s_barrier
	s_add_i32 s0, s45, 1
	s_cmp_ge_u32 s0, s19
	s_cbranch_scc1 .Lgf_skipKB
	s_add_i32 m0, s46, 0
	s_nop 0
	global_load_lds_dwordx4 v[214:215], off
	global_load_lds_dwordx4 v[216:217], off offset:1024
	v_lshl_add_u64 v[214:215], v[214:215], 0, s[20:21]
	v_lshl_add_u64 v[216:217], v[216:217], 0, s[20:21]

; #define MFMA(a, b, c) __builtin_amdgcn_mfma_f32_32x32x16_bf16((a), (b), (c), 0, 0, 0)
; DI unsigned pack2(float a, float b) { f32x2v f = {a, b}; bf16x2v v = __builtin_convertvector(f, bf16x2v); return __builtin_bit_cast(unsigned, v); }
; DI float xhalf(float v) { return __shfl_xor(v, 32); }
;   template <int PAR>
;   DI void step(int t, f32x16 (&cur)[2], f32x16 (&nxt)[2]) {
;     if (t + 1 < nt) sstore_k(PAR ^ 1);
;     if (t > 0) sstore_v(PAR);
;     __syncthreads();
;     if (t + 1 < nt) qk(PAR ^ 1, nxt);
;     float mx = fmaxf(cur[0][0], cur[1][0]);
; #pragma unroll
;     for (int i = 1; i < 16; ++i) mx = fmaxf(fmaxf(cur[0][i], cur[1][i]), mx);
;     if (__builtin_amdgcn_ballot_w64(mx > ATT_THR) != 0ull) {
;       asm volatile("" ::: "memory");
;       mx = fmaxf(mx, xhalf(mx));
;       const float want = mref + fmaxf(mx, 0.f);
;       const float mn = __uint_as_float(pack2(want, 0.f) << 16);
;       const float d = mn - mref;
;       const float alpha = __builtin_amdgcn_exp2f(-d);
;       mref = mn;
;       l *= alpha;
; #pragma unroll
;       for (int a = 0; a < 2; ++a)
; #pragma unroll
;         for (int i = 0; i < 16; ++i) { o[a][i] *= alpha; cur[a][i] -= d; nxt[a][i] -= d; }
;       u32x4 q4 = {h == 0 ? (pack2(-mn, 0.f) & 0xffffu) : 0u, 0u, 0u, 0u};
;       qm = __builtin_bit_cast(bf16x8, q4);
;     }
;     float psum = 0.f;
; #pragma unroll
;     for (int kb2 = 0; kb2 < 2; ++kb2)
; #pragma unroll
;       for (int i = 0; i < 16; ++i) { const float pv = __builtin_amdgcn_exp2f(cur[kb2][i]); cur[kb2][i] = pv; psum += pv; }
;     l += psum;
;     if (t + 2 < nt) gload_k(t + 2);
;     if (t + 1 < nt) gload_v(t + 1);
;     const u16* vb = sV + PAR * VBUF + r * GP + h * 8;
; #pragma unroll
;     for (int kb2 = 0; kb2 < 2; ++kb2)
; #pragma unroll
;       for (int s2 = 0; s2 < 2; ++s2) {
;         u32x4 pk = {pack2(cur[kb2][8 * s2], cur[kb2][8 * s2 + 1]), pack2(cur[kb2][8 * s2 + 2], cur[kb2][8 * s2 + 3]),
;                     pack2(cur[kb2][8 * s2 + 4], cur[kb2][8 * s2 + 5]), pack2(cur[kb2][8 * s2 + 6], cur[kb2][8 * s2 + 7])};
;         const bf16x8 pf = __builtin_bit_cast(bf16x8, pk);
; #pragma unroll
;         for (int db = 0; db < 2; ++db) {
;           const bf16x8 a = *(const bf16x8*)(vb + db * 32 * GP + kb2 * 32 + s2 * 16);
;           o[db] = MFMA(a, pf, o[db]);
;         }
;       }
;   }
.Lgf_skipVB:
	ds_read_b128 v[96:99], v156 offset:27648
	ds_read_b128 v[100:103], v156 offset:31744
	ds_read_b128 v[104:107], v157 offset:27648
	ds_read_b128 v[108:111], v157 offset:31744
	v_mfma_f32_32x32x16_bf16 v[48:63], v[112:115], v[144:147], v[48:63]
	ds_read_b128 v[112:115], v158 offset:27648
	v_exp_f32_e32 v95, v95
	v_add_f32_e32 v183, v93, v183
	v_cvt_pk_bf16_f32 v88, v88, v89
	v_add_f32_e32 v182, v94, v182
	v_cvt_pk_bf16_f32 v89, v90, v91
	v_add_f32_e32 v183, v95, v183
	v_mfma_f32_32x32x16_bf16 v[32:47], v[116:119], v[144:147], v[32:47]
	ds_read_b128 v[116:119], v158 offset:31744
	v_cvt_pk_bf16_f32 v90, v92, v93
	v_cvt_pk_bf16_f32 v91, v94, v95
	v_exp_f32_e32 v64, v64
	v_exp_f32_e32 v65, v65
	v_exp_f32_e32 v66, v66
	v_add_f32_e32 v182, v64, v182
	v_mfma_f32_32x32x16_bf16 v[48:63], v[120:123], v[148:151], v[48:63]
	ds_read_b128 v[120:123], v159 offset:27648
	v_exp_f32_e32 v67, v67
	v_add_f32_e32 v183, v65, v183
	v_exp_f32_e32 v68, v68
	v_add_f32_e32 v182, v66, v182
	v_exp_f32_e32 v69, v69
	v_add_f32_e32 v183, v67, v183
	v_mfma_f32_32x32x16_bf16 v[32:47], v[124:127], v[148:151], v[32:47]
	ds_read_b128 v[124:127], v159 offset:31744
	v_exp_f32_e32 v70, v70
	v_add_f32_e32 v182, v68, v182
	v_exp_f32_e32 v71, v71
	v_add_f32_e32 v183, v69, v183
	v_cvt_pk_bf16_f32 v64, v64, v65
	v_add_f32_e32 v182, v70, v182
	s_waitcnt lgkmcnt(4)
	v_mfma_f32_32x32x16_bf16 v[16:31], v[96:99], v[80:83], v[16:31]
	ds_read_b128 v[96:99], v152 offset:9216
	v_cvt_pk_bf16_f32 v65, v66, v67
	v_add_f32_e32 v183, v71, v183
	v_cvt_pk_bf16_f32 v66, v68, v69
	v_cvt_pk_bf16_f32 v67, v70, v71
	v_exp_f32_e32 v72, v72
	v_mfma_f32_32x32x16_bf16 v[0:15], v[100:103], v[80:83], v[0:15]
	ds_read_b128 v[100:103], v152 offset:13312
	v_exp_f32_e32 v73, v73
	v_exp_f32_e32 v74, v74
	v_add_f32_e32 v182, v72, v182
	v_exp_f32_e32 v75, v75
	v_add_f32_e32 v183, v73, v183
	v_mfma_f32_32x32x16_bf16 v[16:31], v[104:107], v[88:91], v[16:31]
	ds_read_b128 v[104:107], v153 offset:9216
	v_exp_f32_e32 v76, v76
	v_add_f32_e32 v182, v74, v182
	v_exp_f32_e32 v77, v77
	v_add_f32_e32 v183, v75, v183
	v_exp_f32_e32 v78, v78
	v_mfma_f32_32x32x16_bf16 v[0:15], v[108:111], v[88:91], v[0:15]
	ds_read_b128 v[108:111], v153 offset:13312
	v_add_f32_e32 v182, v76, v182
	v_exp_f32_e32 v79, v79
	v_add_f32_e32 v183, v77, v183
	v_cvt_pk_bf16_f32 v72, v72, v73
	v_add_f32_e32 v182, v78, v182
	s_waitcnt lgkmcnt(4)
	v_mfma_f32_32x32x16_bf16 v[16:31], v[112:115], v[64:67], v[16:31]
	ds_read_b128 v[112:115], v154 offset:9216
	v_cvt_pk_bf16_f32 v73, v74, v75
	v_add_f32_e32 v183, v79, v183
	v_cvt_pk_bf16_f32 v74, v76, v77
	v_cvt_pk_bf16_f32 v75, v78, v79
	v_max3_f32 v128, v48, v32, v49
	v_mfma_f32_32x32x16_bf16 v[0:15], v[116:119], v[64:67], v[0:15]
	ds_read_b128 v[116:119], v154 offset:13312
	v_max3_f32 v172, v33, v50, v34
	v_max3_f32 v128, v51, v35, v128
	v_max3_f32 v172, v52, v36, v172
	v_max3_f32 v128, v53, v37, v128
	v_max3_f32 v172, v54, v38, v172
	v_mfma_f32_32x32x16_bf16 v[16:31], v[120:123], v[72:75], v[16:31]
	ds_read_b128 v[120:123], v155 offset:9216
	v_max3_f32 v128, v55, v39, v128
	v_max3_f32 v172, v56, v40, v172
	v_max3_f32 v128, v57, v41, v128
	v_max3_f32 v172, v58, v42, v172
	v_max3_f32 v128, v59, v43, v128
	v_mfma_f32_32x32x16_bf16 v[0:15], v[124:127], v[72:75], v[0:15]
	ds_read_b128 v[124:127], v155 offset:13312
	v_max3_f32 v172, v60, v44, v172
	v_max3_f32 v128, v61, v45, v128
	v_max3_f32 v172, v62, v46, v172
	v_max3_f32 v128, v63, v47, v128
	v_max_f32_e32 v128, v128, v172
	v_lshl_add_u64 v[130:131], v[130:131], 0, s[84:85]
	v_lshl_add_u64 v[180:181], v[180:181], 0, s[84:85]
	s_mov_b32 s0, s45
	s_add_i32 s45, s45, 2
	s_cmp_lt_u32 s0, s19
	s_cbranch_scc1 .Lgf_top
	s_branch .Lg_fold

;   DI void qk(int buf, f32x16 (&s)[2]) {
;     ...
;     for (int ks = 0; ks < NKS; ++ks)
; #pragma unroll
;       for (int kb2 = 0; kb2 < 2; ++kb2) {
;         const bf16x8 a = *(const bf16x8*)(kb + kb2 * 32 * KP + ks * 16);
;         s[kb2] = MFMA(a, qf[ks], s[kb2]);
;       }
;     s[0] = MFMA(kone, qm, s[0]);
;     s[1] = MFMA(kone, qm, s[1]);
;   template <int PAR>
;   DI void step(int t, f32x16 (&cur)[2], f32x16 (&nxt)[2]) {
;     if (t + 1 < nt) sstore_k(PAR ^ 1);
;     if (t > 0) sstore_v(PAR);
;     __syncthreads();
;     if (t + 1 < nt) qk(PAR ^ 1, nxt);
;     float mx = fmaxf(cur[0][0], cur[1][0]);
; #pragma unroll
;     for (int i = 1; i < 16; ++i) mx = fmaxf(fmaxf(cur[0][i], cur[1][i]), mx);
;     if (__builtin_amdgcn_ballot_w64(mx > ATT_THR) != 0ull) {
;       asm volatile("" ::: "memory");
;       mx = fmaxf(mx, xhalf(mx));
;       const float want = mref + fmaxf(mx, 0.f);
;       const float mn = __uint_as_float(pack2(want, 0.f) << 16);
;       const float d = mn - mref;
;       const float alpha = __builtin_amdgcn_exp2f(-d);
;       mref = mn;
;       l *= alpha;
; #pragma unroll
;       for (int a = 0; a < 2; ++a)
; #pragma unroll
;         for (int i = 0; i < 16; ++i) { o[a][i] *= alpha; cur[a][i] -= d; nxt[a][i] -= d; }
;       u32x4 q4 = {h == 0 ? (pack2(-mn, 0.f) & 0xffffu) : 0u, 0u, 0u, 0u};
;       qm = __builtin_bit_cast(bf16x8, q4);
;     }
;     float psum = 0.f;
; #pragma unroll
;     for (int kb2 = 0; kb2 < 2; ++kb2)
; #pragma unroll
;       for (int i = 0; i < 16; ++i) { const float pv = __builtin_amdgcn_exp2f(cur[kb2][i]); cur[kb2][i] = pv; psum += pv; }
;     l += psum;
;     if (t + 2 < nt) gload_k(t + 2);
;     if (t + 1 < nt) gload_v(t + 1);
;     const u16* vb = sV + PAR * VBUF + r * GP + h * 8;
; #pragma unroll
;     for (int kb2 = 0; kb2 < 2; ++kb2)
; #pragma unroll
;       for (int s2 = 0; s2 < 2; ++s2) {
;         u32x4 pk = {pack2(cur[kb2][8 * s2], cur[kb2][8 * s2 + 1]), pack2(cur[kb2][8 * s2 + 2], cur[kb2][8 * s2 + 3]),
;                     pack2(cur[kb2][8 * s2 + 4], cur[kb2][8 * s2 + 5]), pack2(cur[kb2][8 * s2 + 6], cur[kb2][8 * s2 + 7])};
;         const bf16x8 pf = __builtin_bit_cast(bf16x8, pk);
; #pragma unroll
;         for (int db = 0; db < 2; ++db) {
;           const bf16x8 a = *(const bf16x8*)(vb + db * 32 * GP + kb2 * 32 + s2 * 16);
;           o[db] = MFMA(a, pf, o[db]);
;         }
;       }
;   }
.Lg_rareA_ret:
	v_exp_f32_e32 v48, v48
	v_exp_f32_e32 v49, v49
	v_exp_f32_e32 v50, v50
	v_add_f32_e32 v182, v48, v182
	v_exp_f32_e32 v51, v51
	v_add_f32_e32 v183, v49, v183
	v_exp_f32_e32 v52, v52
	v_add_f32_e32 v182, v50, v182
	s_waitcnt lgkmcnt(4)
	v_mfma_f32_32x32x16_bf16 v[80:95], v[96:99], v[136:139], 0
	v_exp_f32_e32 v53, v53
	v_add_f32_e32 v183, v51, v183
	v_exp_f32_e32 v54, v54
	v_add_f32_e32 v182, v52, v182
	v_exp_f32_e32 v55, v55
	v_mfma_f32_32x32x16_bf16 v[64:79], v[100:103], v[136:139], 0
	v_add_f32_e32 v183, v53, v183
	v_cvt_pk_bf16_f32 v48, v48, v49
	v_add_f32_e32 v182, v54, v182
	v_cvt_pk_bf16_f32 v49, v50, v51
	v_add_f32_e32 v183, v55, v183
	v_mfma_f32_32x32x16_bf16 v[80:95], v[104:107], v[140:143], v[80:95]
	v_cvt_pk_bf16_f32 v50, v52, v53
	v_cvt_pk_bf16_f32 v51, v54, v55
	v_exp_f32_e32 v56, v56
	v_exp_f32_e32 v57, v57
	v_exp_f32_e32 v58, v58
	v_mfma_f32_32x32x16_bf16 v[64:79], v[108:111], v[140:143], v[64:79]
	v_add_f32_e32 v182, v56, v182
	v_exp_f32_e32 v59, v59
	v_add_f32_e32 v183, v57, v183
	v_exp_f32_e32 v60, v60
	v_add_f32_e32 v182, v58, v182
	s_waitcnt vmcnt(0)
	s_waitcnt lgkmcnt(0)
	s_barrier
	s_add_i32 s0, s45, -1
	s_cmp_ge_u32 s0, s19
	s_cselect_b64 s[14:15], -1, 0
	s_cmp_ge_u32 s45, s19
	s_cbranch_scc1 .Lg_skipKA
	s_add_i32 m0, s46, 9216
	s_nop 0
	global_load_lds_dwordx4 v[214:215], off
	global_load_lds_dwordx4 v[216:217], off offset:1024
	v_lshl_add_u64 v[214:215], v[214:215], 0, s[20:21]
	v_lshl_add_u64 v[216:217], v[216:217], 0, s[20:21]
.Lg_skipKA:
	s_add_i32 m0, s46, 27648
	s_nop 0
	global_load_lds_dwordx4 v[160:161], off
	global_load_lds_dwordx4 v[162:163], off offset:1024
	v_lshl_add_u64 v[160:161], v[160:161], 0, s[84:85]
	v_lshl_add_u64 v[162:163], v[162:163], 0, s[84:85]
	ds_read_b128 v[96:99], v156 offset:18432
	ds_read_b128 v[100:103], v156 offset:22528
	ds_read_b128 v[104:107], v157 offset:18432
	ds_read_b128 v[108:111], v157 offset:22528
	v_mfma_f32_32x32x16_bf16 v[80:95], v[112:115], v[144:147], v[80:95]
	ds_read_b128 v[112:115], v158 offset:18432
	v_exp_f32_e32 v61, v61
	v_add_f32_e32 v183, v59, v183
	v_exp_f32_e32 v62, v62
	v_add_f32_e32 v182, v60, v182
	v_exp_f32_e32 v63, v63
	v_mfma_f32_32x32x16_bf16 v[64:79], v[116:119], v[144:147], v[64:79]
	ds_read_b128 v[116:119], v158 offset:22528
	v_add_f32_e32 v183, v61, v183
	v_cvt_pk_bf16_f32 v56, v56, v57
	v_add_f32_e32 v182, v62, v182
	v_cvt_pk_bf16_f32 v57, v58, v59
	v_add_f32_e32 v183, v63, v183
	v_mfma_f32_32x32x16_bf16 v[80:95], v[120:123], v[148:151], v[80:95]
	ds_read_b128 v[120:123], v159 offset:18432
	v_cvt_pk_bf16_f32 v58, v60, v61
	v_cvt_pk_bf16_f32 v59, v62, v63
	v_exp_f32_e32 v32, v32
	v_exp_f32_e32 v33, v33
	v_exp_f32_e32 v34, v34
	v_mfma_f32_32x32x16_bf16 v[64:79], v[124:127], v[148:151], v[64:79]
	ds_read_b128 v[124:127], v159 offset:22528
	v_add_f32_e32 v182, v32, v182
	v_exp_f32_e32 v35, v35
	v_add_f32_e32 v183, v33, v183
	v_exp_f32_e32 v36, v36
	v_add_f32_e32 v182, v34, v182
	v_mfma_f32_32x32x16_bf16 v[80:95], v[132:135], v[168:171], v[80:95]
	v_exp_f32_e32 v37, v37
	v_add_f32_e32 v183, v35, v183
	v_exp_f32_e32 v38, v38
	v_add_f32_e32 v182, v36, v182
	v_exp_f32_e32 v39, v39
	v_mfma_f32_32x32x16_bf16 v[64:79], v[132:135], v[168:171], v[64:79]
	v_add_f32_e32 v183, v37, v183
	v_cvt_pk_bf16_f32 v32, v32, v33
	v_add_f32_e32 v182, v38, v182
	v_cvt_pk_bf16_f32 v33, v34, v35
	v_add_f32_e32 v183, v39, v183
	s_waitcnt lgkmcnt(4)
	v_mfma_f32_32x32x16_bf16 v[16:31], v[96:99], v[48:51], v[16:31]
	ds_read_b128 v[96:99], v152
	v_cvt_pk_bf16_f32 v34, v36, v37
	v_cvt_pk_bf16_f32 v35, v38, v39
	v_exp_f32_e32 v40, v40
	v_exp_f32_e32 v41, v41
	v_exp_f32_e32 v42, v42
	v_mfma_f32_32x32x16_bf16 v[0:15], v[100:103], v[48:51], v[0:15]
	ds_read_b128 v[100:103], v152 offset:4096
	v_add_f32_e32 v182, v40, v182
	v_exp_f32_e32 v43, v43
	v_add_f32_e32 v183, v41, v183
	v_exp_f32_e32 v44, v44
	v_add_f32_e32 v182, v42, v182
	v_mfma_f32_32x32x16_bf16 v[16:31], v[104:107], v[56:59], v[16:31]
	ds_read_b128 v[104:107], v153
	v_exp_f32_e32 v45, v45
	v_add_f32_e32 v183, v43, v183
	v_exp_f32_e32 v46, v46
	v_add_f32_e32 v182, v44, v182
	v_exp_f32_e32 v47, v47
	v_mfma_f32_32x32x16_bf16 v[0:15], v[108:111], v[56:59], v[0:15]
	ds_read_b128 v[108:111], v153 offset:4096
	v_add_f32_e32 v183, v45, v183
	v_cvt_pk_bf16_f32 v40, v40, v41
	v_add_f32_e32 v182, v46, v182
	v_cvt_pk_bf16_f32 v41, v42, v43
	v_add_f32_e32 v183, v47, v183
	s_waitcnt lgkmcnt(4)
	v_mfma_f32_32x32x16_bf16 v[16:31], v[112:115], v[32:35], v[16:31]
	ds_read_b128 v[112:115], v154
	v_cvt_pk_bf16_f32 v42, v44, v45
	v_cvt_pk_bf16_f32 v43, v46, v47
	v_max3_f32 v128, v80, v64, v81
	v_max3_f32 v172, v65, v82, v66
	v_max3_f32 v128, v83, v67, v128
	v_mfma_f32_32x32x16_bf16 v[0:15], v[116:119], v[32:35], v[0:15]
	ds_read_b128 v[116:119], v154 offset:4096
	v_max3_f32 v172, v84, v68, v172
	v_max3_f32 v128, v85, v69, v128
	v_max3_f32 v172, v86, v70, v172
	v_max3_f32 v128, v87, v71, v128
	v_max3_f32 v172, v88, v72, v172
	v_mfma_f32_32x32x16_bf16 v[16:31], v[120:123], v[40:43], v[16:31]
	ds_read_b128 v[120:123], v155
	v_max3_f32 v128, v89, v73, v128
	v_max3_f32 v172, v90, v74, v172
	v_max3_f32 v128, v91, v75, v128
	v_max3_f32 v172, v92, v76, v172
	v_mfma_f32_32x32x16_bf16 v[0:15], v[124:127], v[40:43], v[0:15]
	ds_read_b128 v[124:127], v155 offset:4096
	v_max3_f32 v128, v93, v77, v128
	v_max3_f32 v172, v94, v78, v172
	v_max3_f32 v128, v95, v79, v128
	v_max_f32_e32 v128, v128, v172
	v_cmp_lt_f32_e32 vcc, s65, v128
	s_cbranch_vccnz .Lg_rareB
.Lg_rareB_ret:
	v_exp_f32_e32 v80, v80
	v_exp_f32_e32 v81, v81
	v_exp_f32_e32 v82, v82
	v_add_f32_e32 v182, v80, v182
	v_exp_f32_e32 v83, v83
	v_add_f32_e32 v183, v81, v183
	v_exp_f32_e32 v84, v84
	v_add_f32_e32 v182, v82, v182
	s_waitcnt lgkmcnt(4)
	v_mfma_f32_32x32x16_bf16 v[48:63], v[96:99], v[136:139], 0
	v_exp_f32_e32 v85, v85
	v_add_f32_e32 v183, v83, v183
	v_exp_f32_e32 v86, v86
	v_add_f32_e32 v182, v84, v182
	v_exp_f32_e32 v87, v87
	v_mfma_f32_32x32x16_bf16 v[32:47], v[100:103], v[136:139], 0
	v_add_f32_e32 v183, v85, v183
	v_cvt_pk_bf16_f32 v80, v80, v81
	v_add_f32_e32 v182, v86, v182
	v_cvt_pk_bf16_f32 v81, v82, v83
	v_add_f32_e32 v183, v87, v183
	v_mfma_f32_32x32x16_bf16 v[48:63], v[104:107], v[140:143], v[48:63]
	v_cvt_pk_bf16_f32 v82, v84, v85
	v_cvt_pk_bf16_f32 v83, v86, v87
	v_exp_f32_e32 v88, v88
	v_exp_f32_e32 v89, v89
	v_exp_f32_e32 v90, v90
	v_mfma_f32_32x32x16_bf16 v[32:47], v[108:111], v[140:143], v[32:47]
	v_add_f32_e32 v182, v88, v182
	v_exp_f32_e32 v91, v91
	v_add_f32_e32 v183, v89, v183
	v_exp_f32_e32 v92, v92
	v_add_f32_e32 v182, v90, v182
	s_waitcnt vmcnt(0)
	s_waitcnt lgkmcnt(0)
	s_barrier
	s_add_i32 s0, s45, 1
	s_cmp_ge_u32 s0, s19
	s_cbranch_scc1 .Lg_skipKB
	s_add_i32 m0, s46, 0
	s_nop 0
	global_load_lds_dwordx4 v[214:215], off
	global_load_lds_dwordx4 v[216:217], off offset:1024
	v_lshl_add_u64 v[214:215], v[214:215], 0, s[20:21]
	v_lshl_add_u64 v[216:217], v[216:217], 0, s[20:21]

;   DI void qk(int buf, f32x16 (&s)[2]) {
;     ...
;     for (int ks = 0; ks < NKS; ++ks)
; #pragma unroll
;       for (int kb2 = 0; kb2 < 2; ++kb2) {
;         const bf16x8 a = *(const bf16x8*)(kb + kb2 * 32 * KP + ks * 16);
;         s[kb2] = MFMA(a, qf[ks], s[kb2]);
;       }
;     s[0] = MFMA(kone, qm, s[0]);
;     s[1] = MFMA(kone, qm, s[1]);
;   template <int PAR>
;   DI void step(int t, f32x16 (&cur)[2], f32x16 (&nxt)[2]) {
;     if (t + 1 < nt) sstore_k(PAR ^ 1);
;     if (t > 0) sstore_v(PAR);
;     __syncthreads();
;     if (t + 1 < nt) qk(PAR ^ 1, nxt);
;     float mx = fmaxf(cur[0][0], cur[1][0]);
; #pragma unroll
;     for (int i = 1; i < 16; ++i) mx = fmaxf(fmaxf(cur[0][i], cur[1][i]), mx);
;     if (__builtin_amdgcn_ballot_w64(mx > ATT_THR) != 0ull) {
;       asm volatile("" ::: "memory");
;       mx = fmaxf(mx, xhalf(mx));
;       const float want = mref + fmaxf(mx, 0.f);
;       const float mn = __uint_as_float(pack2(want, 0.f) << 16);
;       const float d = mn - mref;
;       const float alpha = __builtin_amdgcn_exp2f(-d);
;       mref = mn;
;       l *= alpha;
; #pragma unroll
;       for (int a = 0; a < 2; ++a)
; #pragma unroll
;         for (int i = 0; i < 16; ++i) { o[a][i] *= alpha; cur[a][i] -= d; nxt[a][i] -= d; }
;       u32x4 q4 = {h == 0 ? (pack2(-mn, 0.f) & 0xffffu) : 0u, 0u, 0u, 0u};
;       qm = __builtin_bit_cast(bf16x8, q4);
;     }
;     float psum = 0.f;
; #pragma unroll
;     for (int kb2 = 0; kb2 < 2; ++kb2)
; #pragma unroll
;       for (int i = 0; i < 16; ++i) { const float pv = __builtin_amdgcn_exp2f(cur[kb2][i]); cur[kb2][i] = pv; psum += pv; }
;     l += psum;
;     if (t + 2 < nt) gload_k(t + 2);
;     if (t + 1 < nt) gload_v(t + 1);
;     const u16* vb = sV + PAR * VBUF + r * GP + h * 8;
; #pragma unroll
;     for (int kb2 = 0; kb2 < 2; ++kb2)
; #pragma unroll
;       for (int s2 = 0; s2 < 2; ++s2) {
;         u32x4 pk = {pack2(cur[kb2][8 * s2], cur[kb2][8 * s2 + 1]), pack2(cur[kb2][8 * s2 + 2], cur[kb2][8 * s2 + 3]),
;                     pack2(cur[kb2][8 * s2 + 4], cur[kb2][8 * s2 + 5]), pack2(cur[kb2][8 * s2 + 6], cur[kb2][8 * s2 + 7])};
;         const bf16x8 pf = __builtin_bit_cast(bf16x8, pk);
; #pragma unroll
;         for (int db = 0; db < 2; ++db) {
;           const bf16x8 a = *(const bf16x8*)(vb + db * 32 * GP + kb2 * 32 + s2 * 16);
;           o[db] = MFMA(a, pf, o[db]);
;         }
;       }
;   }
.Lg_skipVB:
	ds_read_b128 v[96:99], v156 offset:27648
	ds_read_b128 v[100:103], v156 offset:31744
	ds_read_b128 v[104:107], v157 offset:27648
	ds_read_b128 v[108:111], v157 offset:31744
	v_mfma_f32_32x32x16_bf16 v[48:63], v[112:115], v[144:147], v[48:63]
	ds_read_b128 v[112:115], v158 offset:27648
	v_exp_f32_e32 v93, v93
	v_add_f32_e32 v183, v91, v183
	v_exp_f32_e32 v94, v94
	v_add_f32_e32 v182, v92, v182
	v_exp_f32_e32 v95, v95
	v_mfma_f32_32x32x16_bf16 v[32:47], v[116:119], v[144:147], v[32:47]
	ds_read_b128 v[116:119], v158 offset:31744
	v_add_f32_e32 v183, v93, v183
	v_cvt_pk_bf16_f32 v88, v88, v89
	v_add_f32_e32 v182, v94, v182
	v_cvt_pk_bf16_f32 v89, v90, v91
	v_add_f32_e32 v183, v95, v183
	v_mfma_f32_32x32x16_bf16 v[48:63], v[120:123], v[148:151], v[48:63]
	ds_read_b128 v[120:123], v159 offset:27648
	v_cvt_pk_bf16_f32 v90, v92, v93
	v_cvt_pk_bf16_f32 v91, v94, v95
	v_exp_f32_e32 v64, v64
	v_exp_f32_e32 v65, v65
	v_exp_f32_e32 v66, v66
	v_mfma_f32_32x32x16_bf16 v[32:47], v[124:127], v[148:151], v[32:47]
	ds_read_b128 v[124:127], v159 offset:31744
	v_add_f32_e32 v182, v64, v182
	v_exp_f32_e32 v67, v67
	v_add_f32_e32 v183, v65, v183
	v_exp_f32_e32 v68, v68
	v_add_f32_e32 v182, v66, v182
	v_mfma_f32_32x32x16_bf16 v[48:63], v[132:135], v[168:171], v[48:63]
	v_exp_f32_e32 v69, v69
	v_add_f32_e32 v183, v67, v183
	v_exp_f32_e32 v70, v70
	v_add_f32_e32 v182, v68, v182
	v_exp_f32_e32 v71, v71
	v_mfma_f32_32x32x16_bf16 v[32:47], v[132:135], v[168:171], v[32:47]
	v_add_f32_e32 v183, v69, v183
	v_cvt_pk_bf16_f32 v64, v64, v65
	v_add_f32_e32 v182, v70, v182
	v_cvt_pk_bf16_f32 v65, v66, v67
	v_add_f32_e32 v183, v71, v183
	s_waitcnt lgkmcnt(4)
	v_mfma_f32_32x32x16_bf16 v[16:31], v[96:99], v[80:83], v[16:31]
	ds_read_b128 v[96:99], v152 offset:9216
	v_cvt_pk_bf16_f32 v66, v68, v69
	v_cvt_pk_bf16_f32 v67, v70, v71
	v_exp_f32_e32 v72, v72
	v_exp_f32_e32 v73, v73
	v_exp_f32_e32 v74, v74
	v_mfma_f32_32x32x16_bf16 v[0:15], v[100:103], v[80:83], v[0:15]
	ds_read_b128 v[100:103], v152 offset:13312
	v_add_f32_e32 v182, v72, v182
	v_exp_f32_e32 v75, v75
	v_add_f32_e32 v183, v73, v183
	v_exp_f32_e32 v76, v76
	v_add_f32_e32 v182, v74, v182
	v_mfma_f32_32x32x16_bf16 v[16:31], v[104:107], v[88:91], v[16:31]
	ds_read_b128 v[104:107], v153 offset:9216
	v_exp_f32_e32 v77, v77
	v_add_f32_e32 v183, v75, v183
	v_exp_f32_e32 v78, v78
	v_add_f32_e32 v182, v76, v182
	v_exp_f32_e32 v79, v79
	v_mfma_f32_32x32x16_bf16 v[0:15], v[108:111], v[88:91], v[0:15]
	ds_read_b128 v[108:111], v153 offset:13312
	v_add_f32_e32 v183, v77, v183
	v_cvt_pk_bf16_f32 v72, v72, v73
	v_add_f32_e32 v182, v78, v182
	v_cvt_pk_bf16_f32 v73, v74, v75
	v_add_f32_e32 v183, v79, v183
	s_waitcnt lgkmcnt(4)
	v_mfma_f32_32x32x16_bf16 v[16:31], v[112:115], v[64:67], v[16:31]
	ds_read_b128 v[112:115], v154 offset:9216
	v_cvt_pk_bf16_f32 v74, v76, v77
	v_cvt_pk_bf16_f32 v75, v78, v79
	v_max3_f32 v128, v48, v32, v49
	v_max3_f32 v172, v33, v50, v34
	v_max3_f32 v128, v51, v35, v128
	v_mfma_f32_32x32x16_bf16 v[0:15], v[116:119], v[64:67], v[0:15]
	ds_read_b128 v[116:119], v154 offset:13312
	v_max3_f32 v172, v52, v36, v172
	v_max3_f32 v128, v53, v37, v128
	v_max3_f32 v172, v54, v38, v172
	v_max3_f32 v128, v55, v39, v128
	v_max3_f32 v172, v56, v40, v172
	v_mfma_f32_32x32x16_bf16 v[16:31], v[120:123], v[72:75], v[16:31]
	ds_read_b128 v[120:123], v155 offset:9216
	v_max3_f32 v128, v57, v41, v128
	v_max3_f32 v172, v58, v42, v172
	v_max3_f32 v128, v59, v43, v128
	v_max3_f32 v172, v60, v44, v172
	v_mfma_f32_32x32x16_bf16 v[0:15], v[124:127], v[72:75], v[0:15]
	ds_read_b128 v[124:127], v155 offset:13312
	v_max3_f32 v128, v61, v45, v128
	v_max3_f32 v172, v62, v46, v172
	v_max3_f32 v128, v63, v47, v128
	v_max_f32_e32 v128, v128, v172
	v_lshl_add_u64 v[130:131], v[130:131], 0, s[84:85]
	v_lshl_add_u64 v[180:181], v[180:181], 0, s[84:85]
	s_mov_b32 s0, s45
	s_add_i32 s45, s45, 2
	s_cmp_lt_u32 s0, s19
	s_cbranch_scc1 .LBB0_238
	s_branch .Lg_fold

; #define MFMA(a, b, c) __builtin_amdgcn_mfma_f32_32x32x16_bf16((a), (b), (c), 0, 0, 0)
; DI unsigned pack2(float a, float b) { f32x2v f = {a, b}; bf16x2v v = __builtin_convertvector(f, bf16x2v); return __builtin_bit_cast(unsigned, v); }
; DI float xhalf(float v) { return __shfl_xor(v, 32); }
;   template <int PAR>
;   DI void step(int t, f32x16 (&cur)[2], f32x16 (&nxt)[2]) {
;     if (t + 1 < nt) sstore_k(PAR ^ 1);
;     if (t > 0) sstore_v(PAR);
;     __syncthreads();
;     if (t + 1 < nt) qk(PAR ^ 1, nxt);
;     float mx = fmaxf(cur[0][0], cur[1][0]);
; #pragma unroll
;     for (int i = 1; i < 16; ++i) mx = fmaxf(fmaxf(cur[0][i], cur[1][i]), mx);
;     if (__builtin_amdgcn_ballot_w64(mx > ATT_THR) != 0ull) {
;       asm volatile("" ::: "memory");
;       mx = fmaxf(mx, xhalf(mx));
;       const float want = mref + fmaxf(mx, 0.f);
;       const float mn = __uint_as_float(pack2(want, 0.f) << 16);
;       const float d = mn - mref;
;       const float alpha = __builtin_amdgcn_exp2f(-d);
;       mref = mn;
;       l *= alpha;
; #pragma unroll
;       for (int a = 0; a < 2; ++a)
; #pragma unroll
;         for (int i = 0; i < 16; ++i) { o[a][i] *= alpha; cur[a][i] -= d; nxt[a][i] -= d; }
;       u32x4 q4 = {h == 0 ? (pack2(-mn, 0.f) & 0xffffu) : 0u, 0u, 0u, 0u};
;       qm = __builtin_bit_cast(bf16x8, q4);
;     }
;     float psum = 0.f;
; #pragma unroll
;     for (int kb2 = 0; kb2 < 2; ++kb2)
; #pragma unroll
;       for (int i = 0; i < 16; ++i) { const float pv = __builtin_amdgcn_exp2f(cur[kb2][i]); cur[kb2][i] = pv; psum += pv; }
;     l += psum;
;     if (t + 2 < nt) gload_k(t + 2);
;     if (t + 1 < nt) gload_v(t + 1);
;     const u16* vb = sV + PAR * VBUF + r * GP + h * 8;
; #pragma unroll
;     for (int kb2 = 0; kb2 < 2; ++kb2)
; #pragma unroll
;       for (int s2 = 0; s2 < 2; ++s2) {
;         u32x4 pk = {pack2(cur[kb2][8 * s2], cur[kb2][8 * s2 + 1]), pack2(cur[kb2][8 * s2 + 2], cur[kb2][8 * s2 + 3]),
;                     pack2(cur[kb2][8 * s2 + 4], cur[kb2][8 * s2 + 5]), pack2(cur[kb2][8 * s2 + 6], cur[kb2][8 * s2 + 7])};
;         const bf16x8 pf = __builtin_bit_cast(bf16x8, pk);
; #pragma unroll
;         for (int db = 0; db < 2; ++db) {
;           const bf16x8 a = *(const bf16x8*)(vb + db * 32 * GP + kb2 * 32 + s2 * 16);
;           o[db] = MFMA(a, pf, o[db]);
;         }
;       }
;   }
.Lmf_rareA_ret:
	v_exp_f32_e32 v48, v48
	v_exp_f32_e32 v49, v49
	v_exp_f32_e32 v50, v50
	v_add_f32_e32 v238, v48, v238
	v_exp_f32_e32 v51, v51
	v_add_f32_e32 v239, v49, v239
	v_exp_f32_e32 v52, v52
	v_add_f32_e32 v238, v50, v238
	s_waitcnt lgkmcnt(0)
	v_mfma_f32_32x32x16_bf16 v[80:95], v[96:99], v[136:139], 0
	ds_read_b128 v[96:99], v164 offset:21504
	v_exp_f32_e32 v53, v53
	v_add_f32_e32 v239, v51, v239
	v_exp_f32_e32 v54, v54
	v_add_f32_e32 v238, v52, v238
	v_exp_f32_e32 v55, v55
	v_mfma_f32_32x32x16_bf16 v[64:79], v[100:103], v[136:139], 0
	ds_read_b128 v[100:103], v164 offset:23552
	v_add_f32_e32 v239, v53, v239
	v_cvt_pk_bf16_f32 v48, v48, v49
	v_add_f32_e32 v238, v54, v238
	v_cvt_pk_bf16_f32 v49, v50, v51
	v_add_f32_e32 v239, v55, v239
	v_mfma_f32_32x32x16_bf16 v[80:95], v[104:107], v[140:143], v[80:95]
	ds_read_b128 v[104:107], v165 offset:21504
	v_cvt_pk_bf16_f32 v50, v52, v53
	v_cvt_pk_bf16_f32 v51, v54, v55
	v_exp_f32_e32 v56, v56
	v_exp_f32_e32 v57, v57
	v_exp_f32_e32 v58, v58
	v_mfma_f32_32x32x16_bf16 v[64:79], v[108:111], v[140:143], v[64:79]
	ds_read_b128 v[108:111], v165 offset:23552
	v_add_f32_e32 v238, v56, v238
	v_exp_f32_e32 v59, v59
	v_add_f32_e32 v239, v57, v239
	v_exp_f32_e32 v60, v60
	v_add_f32_e32 v238, v58, v238
	s_waitcnt vmcnt(0)
	s_waitcnt lgkmcnt(0)
	s_barrier
	s_add_i32 s0, s31, -1
	s_cmp_ge_u32 s0, s19
	s_cselect_b64 s[14:15], -1, 0
	s_cmp_ge_u32 s31, s19
	s_cbranch_scc1 .Lmf_skipKA
	s_add_i32 m0, s44, 13312
	s_nop 0
	global_load_lds_dwordx4 v[170:171], off
	global_load_lds_dwordx4 v[172:173], off offset:1024
	s_add_i32 m0, s45, 21504
	s_nop 0
	global_load_lds_dwordx4 v[174:175], off
	v_lshl_add_u64 v[170:171], v[170:171], 0, s[20:21]
	v_lshl_add_u64 v[172:173], v[172:173], 0, s[20:21]
	s_mov_b64 s[0:1], 0x1000
	v_lshl_add_u64 v[174:175], v[174:175], 0, s[0:1]
;   DI void qk(int buf, f32x16 (&s)[2]) {
;     ...
;     for (int ks = 0; ks < NKS; ++ks)
; #pragma unroll
;       for (int kb2 = 0; kb2 < 2; ++kb2) {
;         const bf16x8 a = *(const bf16x8*)(kb + kb2 * 32 * KP + ks * 16);
;         s[kb2] = MFMA(a, qf[ks], s[kb2]);
;       }
;     s[0] = MFMA(kone, qm, s[0]);
;     s[1] = MFMA(kone, qm, s[1]);
;   template <int PAR>
;   DI void step(int t, f32x16 (&cur)[2], f32x16 (&nxt)[2]) {
;     if (t + 1 < nt) sstore_k(PAR ^ 1);
;     if (t > 0) sstore_v(PAR);
;     __syncthreads();
;     if (t + 1 < nt) qk(PAR ^ 1, nxt);
;     float mx = fmaxf(cur[0][0], cur[1][0]);
; #pragma unroll
;     for (int i = 1; i < 16; ++i) mx = fmaxf(fmaxf(cur[0][i], cur[1][i]), mx);
;     if (__builtin_amdgcn_ballot_w64(mx > ATT_THR) != 0ull) {
;       asm volatile("" ::: "memory");
;       mx = fmaxf(mx, xhalf(mx));
;       const float want = mref + fmaxf(mx, 0.f);
;       const float mn = __uint_as_float(pack2(want, 0.f) << 16);
;       const float d = mn - mref;
;       const float alpha = __builtin_amdgcn_exp2f(-d);
;       mref = mn;
;       l *= alpha;
; #pragma unroll
;       for (int a = 0; a < 2; ++a)
; #pragma unroll
;         for (int i = 0; i < 16; ++i) { o[a][i] *= alpha; cur[a][i] -= d; nxt[a][i] -= d; }
;       u32x4 q4 = {h == 0 ? (pack2(-mn, 0.f) & 0xffffu) : 0u, 0u, 0u, 0u};
;       qm = __builtin_bit_cast(bf16x8, q4);
;     }
;     float psum = 0.f;
; #pragma unroll
;     for (int kb2 = 0; kb2 < 2; ++kb2)
; #pragma unroll
;       for (int i = 0; i < 16; ++i) { const float pv = __builtin_amdgcn_exp2f(cur[kb2][i]); cur[kb2][i] = pv; psum += pv; }
;     l += psum;
;     if (t + 2 < nt) gload_k(t + 2);
;     if (t + 1 < nt) gload_v(t + 1);
;     const u16* vb = sV + PAR * VBUF + r * GP + h * 8;
; #pragma unroll
;     for (int kb2 = 0; kb2 < 2; ++kb2)
; #pragma unroll
;       for (int s2 = 0; s2 < 2; ++s2) {
;         u32x4 pk = {pack2(cur[kb2][8 * s2], cur[kb2][8 * s2 + 1]), pack2(cur[kb2][8 * s2 + 2], cur[kb2][8 * s2 + 3]),
;                     pack2(cur[kb2][8 * s2 + 4], cur[kb2][8 * s2 + 5]), pack2(cur[kb2][8 * s2 + 6], cur[kb2][8 * s2 + 7])};
;         const bf16x8 pf = __builtin_bit_cast(bf16x8, pk);
; #pragma unroll
;         for (int db = 0; db < 2; ++db) {
;           const bf16x8 a = *(const bf16x8*)(vb + db * 32 * GP + kb2 * 32 + s2 * 16);
;           o[db] = MFMA(a, pf, o[db]);
;         }
;       }
;   }
.Lmf_skipKA:
	s_add_i32 m0, s44, 36864
	s_nop 0
	global_load_lds_dwordx4 v[176:177], off
	global_load_lds_dwordx4 v[178:179], off offset:1024
	v_mfma_f32_32x32x16_bf16 v[80:95], v[112:115], v[144:147], v[80:95]
	ds_read_b128 v[112:115], v166 offset:25600
	v_exp_f32_e32 v61, v61
	v_add_f32_e32 v239, v59, v239
	v_exp_f32_e32 v62, v62
	v_add_f32_e32 v238, v60, v238
	v_exp_f32_e32 v63, v63
	v_mfma_f32_32x32x16_bf16 v[64:79], v[116:119], v[144:147], v[64:79]
	ds_read_b128 v[116:119], v166 offset:29696
	v_add_f32_e32 v239, v61, v239
	v_cvt_pk_bf16_f32 v56, v56, v57
	v_add_f32_e32 v238, v62, v238
	v_cvt_pk_bf16_f32 v57, v58, v59
	v_add_f32_e32 v239, v63, v239
	v_mfma_f32_32x32x16_bf16 v[80:95], v[120:123], v[148:151], v[80:95]
	ds_read_b128 v[120:123], v167 offset:25600
	v_cvt_pk_bf16_f32 v58, v60, v61
	v_cvt_pk_bf16_f32 v59, v62, v63
	v_exp_f32_e32 v32, v32
	v_exp_f32_e32 v33, v33
	v_exp_f32_e32 v34, v34
	v_mfma_f32_32x32x16_bf16 v[64:79], v[124:127], v[148:151], v[64:79]
	ds_read_b128 v[124:127], v167 offset:29696
	v_add_f32_e32 v238, v32, v238
	v_exp_f32_e32 v35, v35
	v_add_f32_e32 v239, v33, v239
	v_exp_f32_e32 v36, v36
	v_add_f32_e32 v238, v34, v238
	v_mfma_f32_32x32x16_bf16 v[80:95], v[96:99], v[152:155], v[80:95]
	ds_read_b128 v[96:99], v168 offset:25600
	v_exp_f32_e32 v37, v37
	v_add_f32_e32 v239, v35, v239
	v_exp_f32_e32 v38, v38
	v_add_f32_e32 v238, v36, v238
	v_mfma_f32_32x32x16_bf16 v[64:79], v[100:103], v[152:155], v[64:79]
	ds_read_b128 v[100:103], v168 offset:29696
	v_exp_f32_e32 v39, v39
	v_add_f32_e32 v239, v37, v239
	v_cvt_pk_bf16_f32 v32, v32, v33
	v_add_f32_e32 v238, v38, v238
	v_mfma_f32_32x32x16_bf16 v[80:95], v[104:107], v[156:159], v[80:95]
	ds_read_b128 v[104:107], v169 offset:25600
	v_cvt_pk_bf16_f32 v33, v34, v35
	v_add_f32_e32 v239, v39, v239
	v_cvt_pk_bf16_f32 v34, v36, v37
	v_cvt_pk_bf16_f32 v35, v38, v39
	v_mfma_f32_32x32x16_bf16 v[64:79], v[108:111], v[156:159], v[64:79]
	ds_read_b128 v[108:111], v169 offset:29696
	v_exp_f32_e32 v40, v40
	v_exp_f32_e32 v41, v41
	v_exp_f32_e32 v42, v42
	v_add_f32_e32 v238, v40, v238
	s_waitcnt lgkmcnt(4)
	v_mfma_f32_32x32x16_bf16 v[16:31], v[112:115], v[48:51], v[16:31]
	ds_read_b128 v[112:115], v162
	v_exp_f32_e32 v43, v43
	v_add_f32_e32 v239, v41, v239
	v_exp_f32_e32 v44, v44
	v_add_f32_e32 v238, v42, v238
	v_mfma_f32_32x32x16_bf16 v[0:15], v[116:119], v[48:51], v[0:15]
	ds_read_b128 v[116:119], v162 offset:4096
	v_exp_f32_e32 v45, v45
	v_add_f32_e32 v239, v43, v239
	v_exp_f32_e32 v46, v46
	v_add_f32_e32 v238, v44, v238
	v_mfma_f32_32x32x16_bf16 v[16:31], v[120:123], v[56:59], v[16:31]
	ds_read_b128 v[120:123], v163
	v_exp_f32_e32 v47, v47
	v_add_f32_e32 v239, v45, v239
	v_cvt_pk_bf16_f32 v40, v40, v41
	v_add_f32_e32 v238, v46, v238
	v_mfma_f32_32x32x16_bf16 v[0:15], v[124:127], v[56:59], v[0:15]
	ds_read_b128 v[124:127], v163 offset:4096
	v_cvt_pk_bf16_f32 v41, v42, v43
	v_add_f32_e32 v239, v47, v239
	v_cvt_pk_bf16_f32 v42, v44, v45
	v_cvt_pk_bf16_f32 v43, v46, v47
	s_waitcnt lgkmcnt(4)
	v_mfma_f32_32x32x16_bf16 v[16:31], v[96:99], v[32:35], v[16:31]
	ds_read_b128 v[96:99], v160
	v_max3_f32 v240, v80, v64, v81
	v_max3_f32 v241, v65, v82, v66
	v_max3_f32 v240, v83, v67, v240
	v_max3_f32 v241, v84, v68, v241
	v_mfma_f32_32x32x16_bf16 v[0:15], v[100:103], v[32:35], v[0:15]
	ds_read_b128 v[100:103], v160 offset:4096
	v_max3_f32 v240, v85, v69, v240
	v_max3_f32 v241, v86, v70, v241
	v_max3_f32 v240, v87, v71, v240
	v_max3_f32 v241, v88, v72, v241
	v_mfma_f32_32x32x16_bf16 v[16:31], v[104:107], v[40:43], v[16:31]
	ds_read_b128 v[104:107], v161
	v_max3_f32 v240, v89, v73, v240
	v_max3_f32 v241, v90, v74, v241
	v_max3_f32 v240, v91, v75, v240
	v_max3_f32 v241, v92, v76, v241
	v_mfma_f32_32x32x16_bf16 v[0:15], v[108:111], v[40:43], v[0:15]
	ds_read_b128 v[108:111], v161 offset:4096
	v_max3_f32 v240, v93, v77, v240
	v_max3_f32 v241, v94, v78, v241
	v_max3_f32 v240, v95, v79, v240
	v_max_f32_e32 v240, v240, v241
	v_cmp_lt_f32_e32 vcc, s65, v240
	s_cbranch_vccnz .Lmf_rareB
.Lmf_rareB_ret:
	v_exp_f32_e32 v80, v80
	v_exp_f32_e32 v81, v81
	v_exp_f32_e32 v82, v82
	v_add_f32_e32 v238, v80, v238
	v_exp_f32_e32 v83, v83
	v_add_f32_e32 v239, v81, v239
	v_exp_f32_e32 v84, v84
	v_add_f32_e32 v238, v82, v238
	s_waitcnt lgkmcnt(0)
	v_mfma_f32_32x32x16_bf16 v[48:63], v[96:99], v[136:139], 0
	ds_read_b128 v[96:99], v164 offset:8192
	v_exp_f32_e32 v85, v85
	v_add_f32_e32 v239, v83, v239
	v_exp_f32_e32 v86, v86
	v_add_f32_e32 v238, v84, v238
	v_exp_f32_e32 v87, v87
	v_mfma_f32_32x32x16_bf16 v[32:47], v[100:103], v[136:139], 0
	ds_read_b128 v[100:103], v164 offset:10240
	v_add_f32_e32 v239, v85, v239
	v_cvt_pk_bf16_f32 v80, v80, v81
	v_add_f32_e32 v238, v86, v238
	v_cvt_pk_bf16_f32 v81, v82, v83
	v_add_f32_e32 v239, v87, v239
	v_mfma_f32_32x32x16_bf16 v[48:63], v[104:107], v[140:143], v[48:63]
	ds_read_b128 v[104:107], v165 offset:8192
	v_cvt_pk_bf16_f32 v82, v84, v85
	v_cvt_pk_bf16_f32 v83, v86, v87
	v_exp_f32_e32 v88, v88
	v_exp_f32_e32 v89, v89
	v_exp_f32_e32 v90, v90
	v_mfma_f32_32x32x16_bf16 v[32:47], v[108:111], v[140:143], v[32:47]
	ds_read_b128 v[108:111], v165 offset:10240
	v_add_f32_e32 v238, v88, v238
	v_exp_f32_e32 v91, v91
	v_add_f32_e32 v239, v89, v239
	v_exp_f32_e32 v92, v92
	v_add_f32_e32 v238, v90, v238
	s_waitcnt vmcnt(0)
	s_waitcnt lgkmcnt(0)
	s_barrier
	s_add_i32 s0, s31, 1
	s_cmp_ge_u32 s0, s19
	s_cbranch_scc1 .Lmf_skipKB
	s_add_i32 m0, s44, 0
	s_nop 0
	global_load_lds_dwordx4 v[170:171], off
	global_load_lds_dwordx4 v[172:173], off offset:1024
	s_add_i32 m0, s45, 8192
	s_nop 0
	global_load_lds_dwordx4 v[174:175], off
	v_lshl_add_u64 v[170:171], v[170:171], 0, s[20:21]
	v_lshl_add_u64 v[172:173], v[172:173], 0, s[20:21]
	s_mov_b64 s[0:1], 0x1000
	v_lshl_add_u64 v[174:175], v[174:175], 0, s[0:1]

;   DI void qk(int buf, f32x16 (&s)[2]) {
;     ...
;     for (int ks = 0; ks < NKS; ++ks)
; #pragma unroll
;       for (int kb2 = 0; kb2 < 2; ++kb2) {
;         const bf16x8 a = *(const bf16x8*)(kb + kb2 * 32 * KP + ks * 16);
;         s[kb2] = MFMA(a, qf[ks], s[kb2]);
;       }
;     s[0] = MFMA(kone, qm, s[0]);
;     s[1] = MFMA(kone, qm, s[1]);
;   template <int PAR>
;   DI void step(int t, f32x16 (&cur)[2], f32x16 (&nxt)[2]) {
;     if (t + 1 < nt) sstore_k(PAR ^ 1);
;     if (t > 0) sstore_v(PAR);
;     __syncthreads();
;     if (t + 1 < nt) qk(PAR ^ 1, nxt);
;     float mx = fmaxf(cur[0][0], cur[1][0]);
; #pragma unroll
;     for (int i = 1; i < 16; ++i) mx = fmaxf(fmaxf(cur[0][i], cur[1][i]), mx);
;     if (__builtin_amdgcn_ballot_w64(mx > ATT_THR) != 0ull) {
;       asm volatile("" ::: "memory");
;       mx = fmaxf(mx, xhalf(mx));
;       const float want = mref + fmaxf(mx, 0.f);
;       const float mn = __uint_as_float(pack2(want, 0.f) << 16);
;       const float d = mn - mref;
;       const float alpha = __builtin_amdgcn_exp2f(-d);
;       mref = mn;
;       l *= alpha;
; #pragma unroll
;       for (int a = 0; a < 2; ++a)
; #pragma unroll
;         for (int i = 0; i < 16; ++i) { o[a][i] *= alpha; cur[a][i] -= d; nxt[a][i] -= d; }
;       u32x4 q4 = {h == 0 ? (pack2(-mn, 0.f) & 0xffffu) : 0u, 0u, 0u, 0u};
;       qm = __builtin_bit_cast(bf16x8, q4);
;     }
;     float psum = 0.f;
; #pragma unroll
;     for (int kb2 = 0; kb2 < 2; ++kb2)
; #pragma unroll
;       for (int i = 0; i < 16; ++i) { const float pv = __builtin_amdgcn_exp2f(cur[kb2][i]); cur[kb2][i] = pv; psum += pv; }
;     l += psum;
;     if (t + 2 < nt) gload_k(t + 2);
;     if (t + 1 < nt) gload_v(t + 1);
;     const u16* vb = sV + PAR * VBUF + r * GP + h * 8;
; #pragma unroll
;     for (int kb2 = 0; kb2 < 2; ++kb2)
; #pragma unroll
;       for (int s2 = 0; s2 < 2; ++s2) {
;         u32x4 pk = {pack2(cur[kb2][8 * s2], cur[kb2][8 * s2 + 1]), pack2(cur[kb2][8 * s2 + 2], cur[kb2][8 * s2 + 3]),
;                     pack2(cur[kb2][8 * s2 + 4], cur[kb2][8 * s2 + 5]), pack2(cur[kb2][8 * s2 + 6], cur[kb2][8 * s2 + 7])};
;         const bf16x8 pf = __builtin_bit_cast(bf16x8, pk);
; #pragma unroll
;         for (int db = 0; db < 2; ++db) {
;           const bf16x8 a = *(const bf16x8*)(vb + db * 32 * GP + kb2 * 32 + s2 * 16);
;           o[db] = MFMA(a, pf, o[db]);
;         }
;       }
;   }
.Lmf_skipVB:
	v_mfma_f32_32x32x16_bf16 v[48:63], v[112:115], v[144:147], v[48:63]
	ds_read_b128 v[112:115], v166 offset:36864
	v_exp_f32_e32 v93, v93
	v_add_f32_e32 v239, v91, v239
	v_exp_f32_e32 v94, v94
	v_add_f32_e32 v238, v92, v238
	v_exp_f32_e32 v95, v95
	v_mfma_f32_32x32x16_bf16 v[32:47], v[116:119], v[144:147], v[32:47]
	ds_read_b128 v[116:119], v166 offset:40960
	v_add_f32_e32 v239, v93, v239
	v_cvt_pk_bf16_f32 v88, v88, v89
	v_add_f32_e32 v238, v94, v238
	v_cvt_pk_bf16_f32 v89, v90, v91
	v_add_f32_e32 v239, v95, v239
	v_mfma_f32_32x32x16_bf16 v[48:63], v[120:123], v[148:151], v[48:63]
	ds_read_b128 v[120:123], v167 offset:36864
	v_cvt_pk_bf16_f32 v90, v92, v93
	v_cvt_pk_bf16_f32 v91, v94, v95
	v_exp_f32_e32 v64, v64
	v_exp_f32_e32 v65, v65
	v_exp_f32_e32 v66, v66
	v_mfma_f32_32x32x16_bf16 v[32:47], v[124:127], v[148:151], v[32:47]
	ds_read_b128 v[124:127], v167 offset:40960
	v_add_f32_e32 v238, v64, v238
	v_exp_f32_e32 v67, v67
	v_add_f32_e32 v239, v65, v239
	v_exp_f32_e32 v68, v68
	v_add_f32_e32 v238, v66, v238
	v_mfma_f32_32x32x16_bf16 v[48:63], v[96:99], v[152:155], v[48:63]
	ds_read_b128 v[96:99], v168 offset:36864
	v_exp_f32_e32 v69, v69
	v_add_f32_e32 v239, v67, v239
	v_exp_f32_e32 v70, v70
	v_add_f32_e32 v238, v68, v238
	v_mfma_f32_32x32x16_bf16 v[32:47], v[100:103], v[152:155], v[32:47]
	ds_read_b128 v[100:103], v168 offset:40960
	v_exp_f32_e32 v71, v71
	v_add_f32_e32 v239, v69, v239
	v_cvt_pk_bf16_f32 v64, v64, v65
	v_add_f32_e32 v238, v70, v238
	v_mfma_f32_32x32x16_bf16 v[48:63], v[104:107], v[156:159], v[48:63]
	ds_read_b128 v[104:107], v169 offset:36864
	v_cvt_pk_bf16_f32 v65, v66, v67
	v_add_f32_e32 v239, v71, v239
	v_cvt_pk_bf16_f32 v66, v68, v69
	v_cvt_pk_bf16_f32 v67, v70, v71
	v_mfma_f32_32x32x16_bf16 v[32:47], v[108:111], v[156:159], v[32:47]
	ds_read_b128 v[108:111], v169 offset:40960
	v_exp_f32_e32 v72, v72
	v_exp_f32_e32 v73, v73
	v_exp_f32_e32 v74, v74
	v_add_f32_e32 v238, v72, v238
	s_waitcnt lgkmcnt(4)
	v_mfma_f32_32x32x16_bf16 v[16:31], v[112:115], v[80:83], v[16:31]
	ds_read_b128 v[112:115], v162 offset:13312
	v_exp_f32_e32 v75, v75
	v_add_f32_e32 v239, v73, v239
	v_exp_f32_e32 v76, v76
	v_add_f32_e32 v238, v74, v238
	v_mfma_f32_32x32x16_bf16 v[0:15], v[116:119], v[80:83], v[0:15]
	ds_read_b128 v[116:119], v162 offset:17408
	v_exp_f32_e32 v77, v77
	v_add_f32_e32 v239, v75, v239
	v_exp_f32_e32 v78, v78
	v_add_f32_e32 v238, v76, v238
	v_mfma_f32_32x32x16_bf16 v[16:31], v[120:123], v[88:91], v[16:31]
	ds_read_b128 v[120:123], v163 offset:13312
	v_exp_f32_e32 v79, v79
	v_add_f32_e32 v239, v77, v239
	v_cvt_pk_bf16_f32 v72, v72, v73
	v_add_f32_e32 v238, v78, v238
	v_mfma_f32_32x32x16_bf16 v[0:15], v[124:127], v[88:91], v[0:15]
	ds_read_b128 v[124:127], v163 offset:17408
	v_cvt_pk_bf16_f32 v73, v74, v75
	v_add_f32_e32 v239, v79, v239
	v_cvt_pk_bf16_f32 v74, v76, v77
	v_cvt_pk_bf16_f32 v75, v78, v79
	s_waitcnt lgkmcnt(4)
	v_mfma_f32_32x32x16_bf16 v[16:31], v[96:99], v[64:67], v[16:31]
	ds_read_b128 v[96:99], v160 offset:13312
	v_max3_f32 v240, v48, v32, v49
	v_max3_f32 v241, v33, v50, v34
	v_max3_f32 v240, v51, v35, v240
	v_max3_f32 v241, v52, v36, v241
	v_mfma_f32_32x32x16_bf16 v[0:15], v[100:103], v[64:67], v[0:15]
	ds_read_b128 v[100:103], v160 offset:17408
	v_max3_f32 v240, v53, v37, v240
	v_max3_f32 v241, v54, v38, v241
	v_max3_f32 v240, v55, v39, v240
	v_max3_f32 v241, v56, v40, v241
	v_mfma_f32_32x32x16_bf16 v[16:31], v[104:107], v[72:75], v[16:31]
	ds_read_b128 v[104:107], v161 offset:13312
	v_max3_f32 v240, v57, v41, v240
	v_max3_f32 v241, v58, v42, v241
	v_max3_f32 v240, v59, v43, v240
	v_max3_f32 v241, v60, v44, v241
	v_mfma_f32_32x32x16_bf16 v[0:15], v[108:111], v[72:75], v[0:15]
	ds_read_b128 v[108:111], v161 offset:17408
	v_max3_f32 v240, v61, v45, v240
	v_max3_f32 v241, v62, v46, v241
	v_max3_f32 v240, v63, v47, v240
	v_max_f32_e32 v240, v240, v241
	v_lshl_add_u64 v[130:131], v[130:131], 0, s[84:85]
	v_lshl_add_u64 v[220:221], v[220:221], 0, s[84:85]
	s_mov_b32 s0, s31
	s_add_i32 s31, s31, 2
	s_cmp_lt_u32 s0, s19
	s_cbranch_scc1 .Lmf_top
	s_branch .Lm_fold

; #define MFMA(a, b, c) __builtin_amdgcn_mfma_f32_32x32x16_bf16((a), (b), (c), 0, 0, 0)
; DI unsigned pack2(float a, float b) { f32x2v f = {a, b}; bf16x2v v = __builtin_convertvector(f, bf16x2v); return __builtin_bit_cast(unsigned, v); }
; DI float xhalf(float v) { return __shfl_xor(v, 32); }
;   template <int PAR>
;   DI void step(int t, f32x16 (&cur)[2], f32x16 (&nxt)[2]) {
;     if (t + 1 < nt) sstore_k(PAR ^ 1);
;     if (t > 0) sstore_v(PAR);
;     __syncthreads();
;     if (t + 1 < nt) qk(PAR ^ 1, nxt);
;     float mx = fmaxf(cur[0][0], cur[1][0]);
; #pragma unroll
;     for (int i = 1; i < 16; ++i) mx = fmaxf(fmaxf(cur[0][i], cur[1][i]), mx);
;     if (__builtin_amdgcn_ballot_w64(mx > ATT_THR) != 0ull) {
;       asm volatile("" ::: "memory");
;       mx = fmaxf(mx, xhalf(mx));
;       const float want = mref + fmaxf(mx, 0.f);
;       const float mn = __uint_as_float(pack2(want, 0.f) << 16);
;       const float d = mn - mref;
;       const float alpha = __builtin_amdgcn_exp2f(-d);
;       mref = mn;
;       l *= alpha;
; #pragma unroll
;       for (int a = 0; a < 2; ++a)
; #pragma unroll
;         for (int i = 0; i < 16; ++i) { o[a][i] *= alpha; cur[a][i] -= d; nxt[a][i] -= d; }
;       u32x4 q4 = {h == 0 ? (pack2(-mn, 0.f) & 0xffffu) : 0u, 0u, 0u, 0u};
;       qm = __builtin_bit_cast(bf16x8, q4);
;     }
;     float psum = 0.f;
; #pragma unroll
;     for (int kb2 = 0; kb2 < 2; ++kb2)
; #pragma unroll
;       for (int i = 0; i < 16; ++i) { const float pv = __builtin_amdgcn_exp2f(cur[kb2][i]); cur[kb2][i] = pv; psum += pv; }
;     l += psum;
;     if (t + 2 < nt) gload_k(t + 2);
;     if (t + 1 < nt) gload_v(t + 1);
;     const u16* vb = sV + PAR * VBUF + r * GP + h * 8;
; #pragma unroll
;     for (int kb2 = 0; kb2 < 2; ++kb2)
; #pragma unroll
;       for (int s2 = 0; s2 < 2; ++s2) {
;         u32x4 pk = {pack2(cur[kb2][8 * s2], cur[kb2][8 * s2 + 1]), pack2(cur[kb2][8 * s2 + 2], cur[kb2][8 * s2 + 3]),
;                     pack2(cur[kb2][8 * s2 + 4], cur[kb2][8 * s2 + 5]), pack2(cur[kb2][8 * s2 + 6], cur[kb2][8 * s2 + 7])};
;         const bf16x8 pf = __builtin_bit_cast(bf16x8, pk);
; #pragma unroll
;         for (int db = 0; db < 2; ++db) {
;           const bf16x8 a = *(const bf16x8*)(vb + db * 32 * GP + kb2 * 32 + s2 * 16);
;           o[db] = MFMA(a, pf, o[db]);
;         }
;       }
;   }
.Lm_rareA_ret:
	v_exp_f32_e32 v48, v48
	v_exp_f32_e32 v49, v49
	v_exp_f32_e32 v50, v50
	v_add_f32_e32 v238, v48, v238
	v_exp_f32_e32 v51, v51
	v_add_f32_e32 v239, v49, v239
	v_exp_f32_e32 v52, v52
	v_add_f32_e32 v238, v50, v238
	s_waitcnt lgkmcnt(0)
	v_mfma_f32_32x32x16_bf16 v[80:95], v[96:99], v[136:139], 0
	ds_read_b128 v[96:99], v164 offset:21504
	v_exp_f32_e32 v53, v53
	v_add_f32_e32 v239, v51, v239
	v_exp_f32_e32 v54, v54
	v_add_f32_e32 v238, v52, v238
	v_mfma_f32_32x32x16_bf16 v[64:79], v[100:103], v[136:139], 0
	ds_read_b128 v[100:103], v164 offset:23552
	v_exp_f32_e32 v55, v55
	v_add_f32_e32 v239, v53, v239
	v_cvt_pk_bf16_f32 v48, v48, v49
	v_add_f32_e32 v238, v54, v238
	v_mfma_f32_32x32x16_bf16 v[80:95], v[104:107], v[140:143], v[80:95]
	ds_read_b128 v[104:107], v165 offset:21504
	v_cvt_pk_bf16_f32 v49, v50, v51
	v_add_f32_e32 v239, v55, v239
	v_cvt_pk_bf16_f32 v50, v52, v53
	v_cvt_pk_bf16_f32 v51, v54, v55
	v_mfma_f32_32x32x16_bf16 v[64:79], v[108:111], v[140:143], v[64:79]
	ds_read_b128 v[108:111], v165 offset:23552
	v_exp_f32_e32 v56, v56
	v_exp_f32_e32 v57, v57
	v_exp_f32_e32 v58, v58
	v_add_f32_e32 v238, v56, v238
	s_waitcnt vmcnt(0)
	s_waitcnt lgkmcnt(0)
	s_barrier
	s_add_i32 s0, s31, -1
	s_cmp_ge_u32 s0, s19
	s_cselect_b64 s[14:15], -1, 0
	s_cmp_ge_u32 s31, s19
	s_cbranch_scc1 .Lm_skipKA
	s_add_i32 m0, s44, 13312
	s_nop 0
	global_load_lds_dwordx4 v[170:171], off
	global_load_lds_dwordx4 v[172:173], off offset:1024
	s_add_i32 m0, s45, 21504
	s_nop 0
	global_load_lds_dwordx4 v[174:175], off
	v_lshl_add_u64 v[170:171], v[170:171], 0, s[20:21]
	v_lshl_add_u64 v[172:173], v[172:173], 0, s[20:21]
	s_mov_b64 s[0:1], 0x1000
	v_lshl_add_u64 v[174:175], v[174:175], 0, s[0:1]
;   DI void qk(int buf, f32x16 (&s)[2]) {
;     ...
;     for (int ks = 0; ks < NKS; ++ks)
; #pragma unroll
;       for (int kb2 = 0; kb2 < 2; ++kb2) {
;         const bf16x8 a = *(const bf16x8*)(kb + kb2 * 32 * KP + ks * 16);
;         s[kb2] = MFMA(a, qf[ks], s[kb2]);
;       }
;     s[0] = MFMA(kone, qm, s[0]);
;     s[1] = MFMA(kone, qm, s[1]);
;   template <int PAR>
;   DI void step(int t, f32x16 (&cur)[2], f32x16 (&nxt)[2]) {
;     if (t + 1 < nt) sstore_k(PAR ^ 1);
;     if (t > 0) sstore_v(PAR);
;     __syncthreads();
;     if (t + 1 < nt) qk(PAR ^ 1, nxt);
;     float mx = fmaxf(cur[0][0], cur[1][0]);
; #pragma unroll
;     for (int i = 1; i < 16; ++i) mx = fmaxf(fmaxf(cur[0][i], cur[1][i]), mx);
;     if (__builtin_amdgcn_ballot_w64(mx > ATT_THR) != 0ull) {
;       asm volatile("" ::: "memory");
;       mx = fmaxf(mx, xhalf(mx));
;       const float want = mref + fmaxf(mx, 0.f);
;       const float mn = __uint_as_float(pack2(want, 0.f) << 16);
;       const float d = mn - mref;
;       const float alpha = __builtin_amdgcn_exp2f(-d);
;       mref = mn;
;       l *= alpha;
; #pragma unroll
;       for (int a = 0; a < 2; ++a)
; #pragma unroll
;         for (int i = 0; i < 16; ++i) { o[a][i] *= alpha; cur[a][i] -= d; nxt[a][i] -= d; }
;       u32x4 q4 = {h == 0 ? (pack2(-mn, 0.f) & 0xffffu) : 0u, 0u, 0u, 0u};
;       qm = __builtin_bit_cast(bf16x8, q4);
;     }
;     float psum = 0.f;
; #pragma unroll
;     for (int kb2 = 0; kb2 < 2; ++kb2)
; #pragma unroll
;       for (int i = 0; i < 16; ++i) { const float pv = __builtin_amdgcn_exp2f(cur[kb2][i]); cur[kb2][i] = pv; psum += pv; }
;     l += psum;
;     if (t + 2 < nt) gload_k(t + 2);
;     if (t + 1 < nt) gload_v(t + 1);
;     const u16* vb = sV + PAR * VBUF + r * GP + h * 8;
; #pragma unroll
;     for (int kb2 = 0; kb2 < 2; ++kb2)
; #pragma unroll
;       for (int s2 = 0; s2 < 2; ++s2) {
;         u32x4 pk = {pack2(cur[kb2][8 * s2], cur[kb2][8 * s2 + 1]), pack2(cur[kb2][8 * s2 + 2], cur[kb2][8 * s2 + 3]),
;                     pack2(cur[kb2][8 * s2 + 4], cur[kb2][8 * s2 + 5]), pack2(cur[kb2][8 * s2 + 6], cur[kb2][8 * s2 + 7])};
;         const bf16x8 pf = __builtin_bit_cast(bf16x8, pk);
; #pragma unroll
;         for (int db = 0; db < 2; ++db) {
;           const bf16x8 a = *(const bf16x8*)(vb + db * 32 * GP + kb2 * 32 + s2 * 16);
;           o[db] = MFMA(a, pf, o[db]);
;         }
;       }
;   }
.Lm_skipKA:
	s_add_i32 m0, s44, 36864
	s_nop 0
	global_load_lds_dwordx4 v[176:177], off
	global_load_lds_dwordx4 v[178:179], off offset:1024
	v_mfma_f32_32x32x16_bf16 v[80:95], v[112:115], v[144:147], v[80:95]
	ds_read_b128 v[112:115], v166 offset:25600
	v_exp_f32_e32 v59, v59
	v_add_f32_e32 v239, v57, v239
	v_exp_f32_e32 v60, v60
	v_add_f32_e32 v238, v58, v238
	v_mfma_f32_32x32x16_bf16 v[64:79], v[116:119], v[144:147], v[64:79]
	ds_read_b128 v[116:119], v166 offset:29696
	v_exp_f32_e32 v61, v61
	v_add_f32_e32 v239, v59, v239
	v_exp_f32_e32 v62, v62
	v_add_f32_e32 v238, v60, v238
	v_mfma_f32_32x32x16_bf16 v[80:95], v[120:123], v[148:151], v[80:95]
	ds_read_b128 v[120:123], v167 offset:25600
	v_exp_f32_e32 v63, v63
	v_add_f32_e32 v239, v61, v239
	v_cvt_pk_bf16_f32 v56, v56, v57
	v_add_f32_e32 v238, v62, v238
	v_mfma_f32_32x32x16_bf16 v[64:79], v[124:127], v[148:151], v[64:79]
	ds_read_b128 v[124:127], v167 offset:29696
	v_cvt_pk_bf16_f32 v57, v58, v59
	v_add_f32_e32 v239, v63, v239
	v_cvt_pk_bf16_f32 v58, v60, v61
	v_cvt_pk_bf16_f32 v59, v62, v63
	v_mfma_f32_32x32x16_bf16 v[80:95], v[96:99], v[152:155], v[80:95]
	ds_read_b128 v[96:99], v168 offset:25600
	v_exp_f32_e32 v32, v32
	v_exp_f32_e32 v33, v33
	v_exp_f32_e32 v34, v34
	v_add_f32_e32 v238, v32, v238
	v_mfma_f32_32x32x16_bf16 v[64:79], v[100:103], v[152:155], v[64:79]
	ds_read_b128 v[100:103], v168 offset:29696
	v_exp_f32_e32 v35, v35
	v_add_f32_e32 v239, v33, v239
	v_exp_f32_e32 v36, v36
	v_add_f32_e32 v238, v34, v238
	v_mfma_f32_32x32x16_bf16 v[80:95], v[104:107], v[156:159], v[80:95]
	ds_read_b128 v[104:107], v169 offset:25600
	v_exp_f32_e32 v37, v37
	v_add_f32_e32 v239, v35, v239
	v_exp_f32_e32 v38, v38
	v_add_f32_e32 v238, v36, v238
	v_mfma_f32_32x32x16_bf16 v[64:79], v[108:111], v[156:159], v[64:79]
	ds_read_b128 v[108:111], v169 offset:29696
	v_exp_f32_e32 v39, v39
	v_add_f32_e32 v239, v37, v239
	v_cvt_pk_bf16_f32 v32, v32, v33
	v_add_f32_e32 v238, v38, v238
	v_mfma_f32_32x32x16_bf16 v[80:95], v[132:135], v[180:183], v[80:95]
	v_cvt_pk_bf16_f32 v33, v34, v35
	v_add_f32_e32 v239, v39, v239
	v_cvt_pk_bf16_f32 v34, v36, v37
	v_cvt_pk_bf16_f32 v35, v38, v39
	v_mfma_f32_32x32x16_bf16 v[64:79], v[132:135], v[180:183], v[64:79]
	v_exp_f32_e32 v40, v40
	v_exp_f32_e32 v41, v41
	v_exp_f32_e32 v42, v42
	v_add_f32_e32 v238, v40, v238
	s_waitcnt lgkmcnt(4)
	v_mfma_f32_32x32x16_bf16 v[16:31], v[112:115], v[48:51], v[16:31]
	ds_read_b128 v[112:115], v162
	v_exp_f32_e32 v43, v43
	v_add_f32_e32 v239, v41, v239
	v_exp_f32_e32 v44, v44
	v_add_f32_e32 v238, v42, v238
	v_mfma_f32_32x32x16_bf16 v[0:15], v[116:119], v[48:51], v[0:15]
	ds_read_b128 v[116:119], v162 offset:4096
	v_exp_f32_e32 v45, v45
	v_add_f32_e32 v239, v43, v239
	v_exp_f32_e32 v46, v46
	v_add_f32_e32 v238, v44, v238
	v_mfma_f32_32x32x16_bf16 v[16:31], v[120:123], v[56:59], v[16:31]
	ds_read_b128 v[120:123], v163
	v_exp_f32_e32 v47, v47
	v_add_f32_e32 v239, v45, v239
	v_cvt_pk_bf16_f32 v40, v40, v41
	v_add_f32_e32 v238, v46, v238
	v_mfma_f32_32x32x16_bf16 v[0:15], v[124:127], v[56:59], v[0:15]
	ds_read_b128 v[124:127], v163 offset:4096
	v_cvt_pk_bf16_f32 v41, v42, v43
	v_add_f32_e32 v239, v47, v239
	v_cvt_pk_bf16_f32 v42, v44, v45
	v_cvt_pk_bf16_f32 v43, v46, v47
	s_waitcnt lgkmcnt(4)
	v_mfma_f32_32x32x16_bf16 v[16:31], v[96:99], v[32:35], v[16:31]
	ds_read_b128 v[96:99], v160
	v_max3_f32 v240, v80, v64, v81
	v_max3_f32 v241, v65, v82, v66
	v_max3_f32 v240, v83, v67, v240
	v_max3_f32 v241, v84, v68, v241
	v_mfma_f32_32x32x16_bf16 v[0:15], v[100:103], v[32:35], v[0:15]
	ds_read_b128 v[100:103], v160 offset:4096
	v_max3_f32 v240, v85, v69, v240
	v_max3_f32 v241, v86, v70, v241
	v_max3_f32 v240, v87, v71, v240
	v_max3_f32 v241, v88, v72, v241
	v_mfma_f32_32x32x16_bf16 v[16:31], v[104:107], v[40:43], v[16:31]
	ds_read_b128 v[104:107], v161
	v_max3_f32 v240, v89, v73, v240
	v_max3_f32 v241, v90, v74, v241
	v_max3_f32 v240, v91, v75, v240
	v_max3_f32 v241, v92, v76, v241
	v_mfma_f32_32x32x16_bf16 v[0:15], v[108:111], v[40:43], v[0:15]
	ds_read_b128 v[108:111], v161 offset:4096
	v_max3_f32 v240, v93, v77, v240
	v_max3_f32 v241, v94, v78, v241
	v_max3_f32 v240, v95, v79, v240
	v_max_f32_e32 v240, v240, v241
	v_cmp_lt_f32_e32 vcc, s65, v240
	s_cbranch_vccnz .Lm_rareB
.Lm_rareB_ret:
	v_exp_f32_e32 v80, v80
	v_exp_f32_e32 v81, v81
	v_exp_f32_e32 v82, v82
	v_add_f32_e32 v238, v80, v238
	v_exp_f32_e32 v83, v83
	v_add_f32_e32 v239, v81, v239
	v_exp_f32_e32 v84, v84
	v_add_f32_e32 v238, v82, v238
	s_waitcnt lgkmcnt(0)
	v_mfma_f32_32x32x16_bf16 v[48:63], v[96:99], v[136:139], 0
	ds_read_b128 v[96:99], v164 offset:8192
	v_exp_f32_e32 v85, v85
	v_add_f32_e32 v239, v83, v239
	v_exp_f32_e32 v86, v86
	v_add_f32_e32 v238, v84, v238
	v_mfma_f32_32x32x16_bf16 v[32:47], v[100:103], v[136:139], 0
	ds_read_b128 v[100:103], v164 offset:10240
	v_exp_f32_e32 v87, v87
	v_add_f32_e32 v239, v85, v239
	v_cvt_pk_bf16_f32 v80, v80, v81
	v_add_f32_e32 v238, v86, v238
	v_mfma_f32_32x32x16_bf16 v[48:63], v[104:107], v[140:143], v[48:63]
	ds_read_b128 v[104:107], v165 offset:8192
	v_cvt_pk_bf16_f32 v81, v82, v83
	v_add_f32_e32 v239, v87, v239
	v_cvt_pk_bf16_f32 v82, v84, v85
	v_cvt_pk_bf16_f32 v83, v86, v87
	v_mfma_f32_32x32x16_bf16 v[32:47], v[108:111], v[140:143], v[32:47]
	ds_read_b128 v[108:111], v165 offset:10240
	v_exp_f32_e32 v88, v88
	v_exp_f32_e32 v89, v89
	v_exp_f32_e32 v90, v90
	v_add_f32_e32 v238, v88, v238
	s_waitcnt vmcnt(0)
	s_waitcnt lgkmcnt(0)
	s_barrier
	s_add_i32 s0, s31, 1
	s_cmp_ge_u32 s0, s19
	s_cbranch_scc1 .Lm_skipKB
	s_add_i32 m0, s44, 0
	s_nop 0
	global_load_lds_dwordx4 v[170:171], off
	global_load_lds_dwordx4 v[172:173], off offset:1024
	s_add_i32 m0, s45, 8192
	s_nop 0
	global_load_lds_dwordx4 v[174:175], off
	v_lshl_add_u64 v[170:171], v[170:171], 0, s[20:21]
	v_lshl_add_u64 v[172:173], v[172:173], 0, s[20:21]
	s_mov_b64 s[0:1], 0x1000
	v_lshl_add_u64 v[174:175], v[174:175], 0, s[0:1]

;   DI void qk(int buf, f32x16 (&s)[2]) {
;     ...
;     for (int ks = 0; ks < NKS; ++ks)
; #pragma unroll
;       for (int kb2 = 0; kb2 < 2; ++kb2) {
;         const bf16x8 a = *(const bf16x8*)(kb + kb2 * 32 * KP + ks * 16);
;         s[kb2] = MFMA(a, qf[ks], s[kb2]);
;       }
;     s[0] = MFMA(kone, qm, s[0]);
;     s[1] = MFMA(kone, qm, s[1]);
;   template <int PAR>
;   DI void step(int t, f32x16 (&cur)[2], f32x16 (&nxt)[2]) {
;     if (t + 1 < nt) sstore_k(PAR ^ 1);
;     if (t > 0) sstore_v(PAR);
;     __syncthreads();
;     if (t + 1 < nt) qk(PAR ^ 1, nxt);
;     float mx = fmaxf(cur[0][0], cur[1][0]);
; #pragma unroll
;     for (int i = 1; i < 16; ++i) mx = fmaxf(fmaxf(cur[0][i], cur[1][i]), mx);
;     if (__builtin_amdgcn_ballot_w64(mx > ATT_THR) != 0ull) {
;       asm volatile("" ::: "memory");
;       mx = fmaxf(mx, xhalf(mx));
;       const float want = mref + fmaxf(mx, 0.f);
;       const float mn = __uint_as_float(pack2(want, 0.f) << 16);
;       const float d = mn - mref;
;       const float alpha = __builtin_amdgcn_exp2f(-d);
;       mref = mn;
;       l *= alpha;
; #pragma unroll
;       for (int a = 0; a < 2; ++a)
; #pragma unroll
;         for (int i = 0; i < 16; ++i) { o[a][i] *= alpha; cur[a][i] -= d; nxt[a][i] -= d; }
;       u32x4 q4 = {h == 0 ? (pack2(-mn, 0.f) & 0xffffu) : 0u, 0u, 0u, 0u};
;       qm = __builtin_bit_cast(bf16x8, q4);
;     }
;     float psum = 0.f;
; #pragma unroll
;     for (int kb2 = 0; kb2 < 2; ++kb2)
; #pragma unroll
;       for (int i = 0; i < 16; ++i) { const float pv = __builtin_amdgcn_exp2f(cur[kb2][i]); cur[kb2][i] = pv; psum += pv; }
;     l += psum;
;     if (t + 2 < nt) gload_k(t + 2);
;     if (t + 1 < nt) gload_v(t + 1);
;     const u16* vb = sV + PAR * VBUF + r * GP + h * 8;
; #pragma unroll
;     for (int kb2 = 0; kb2 < 2; ++kb2)
; #pragma unroll
;       for (int s2 = 0; s2 < 2; ++s2) {
;         u32x4 pk = {pack2(cur[kb2][8 * s2], cur[kb2][8 * s2 + 1]), pack2(cur[kb2][8 * s2 + 2], cur[kb2][8 * s2 + 3]),
;                     pack2(cur[kb2][8 * s2 + 4], cur[kb2][8 * s2 + 5]), pack2(cur[kb2][8 * s2 + 6], cur[kb2][8 * s2 + 7])};
;         const bf16x8 pf = __builtin_bit_cast(bf16x8, pk);
; #pragma unroll
;         for (int db = 0; db < 2; ++db) {
;           const bf16x8 a = *(const bf16x8*)(vb + db * 32 * GP + kb2 * 32 + s2 * 16);
;           o[db] = MFMA(a, pf, o[db]);
;         }
;       }
;   }
.Lm_skipVB:
	v_mfma_f32_32x32x16_bf16 v[48:63], v[112:115], v[144:147], v[48:63]
	ds_read_b128 v[112:115], v166 offset:36864
	v_exp_f32_e32 v91, v91
	v_add_f32_e32 v239, v89, v239
	v_exp_f32_e32 v92, v92
	v_add_f32_e32 v238, v90, v238
	v_mfma_f32_32x32x16_bf16 v[32:47], v[116:119], v[144:147], v[32:47]
	ds_read_b128 v[116:119], v166 offset:40960
	v_exp_f32_e32 v93, v93
	v_add_f32_e32 v239, v91, v239
	v_exp_f32_e32 v94, v94
	v_add_f32_e32 v238, v92, v238
	v_mfma_f32_32x32x16_bf16 v[48:63], v[120:123], v[148:151], v[48:63]
	ds_read_b128 v[120:123], v167 offset:36864
	v_exp_f32_e32 v95, v95
	v_add_f32_e32 v239, v93, v239
	v_cvt_pk_bf16_f32 v88, v88, v89
	v_add_f32_e32 v238, v94, v238
	v_mfma_f32_32x32x16_bf16 v[32:47], v[124:127], v[148:151], v[32:47]
	ds_read_b128 v[124:127], v167 offset:40960
	v_cvt_pk_bf16_f32 v89, v90, v91
	v_add_f32_e32 v239, v95, v239
	v_cvt_pk_bf16_f32 v90, v92, v93
	v_cvt_pk_bf16_f32 v91, v94, v95
	v_mfma_f32_32x32x16_bf16 v[48:63], v[96:99], v[152:155], v[48:63]
	ds_read_b128 v[96:99], v168 offset:36864
	v_exp_f32_e32 v64, v64
	v_exp_f32_e32 v65, v65
	v_exp_f32_e32 v66, v66
	v_add_f32_e32 v238, v64, v238
	v_mfma_f32_32x32x16_bf16 v[32:47], v[100:103], v[152:155], v[32:47]
	ds_read_b128 v[100:103], v168 offset:40960
	v_exp_f32_e32 v67, v67
	v_add_f32_e32 v239, v65, v239
	v_exp_f32_e32 v68, v68
	v_add_f32_e32 v238, v66, v238
	v_mfma_f32_32x32x16_bf16 v[48:63], v[104:107], v[156:159], v[48:63]
	ds_read_b128 v[104:107], v169 offset:36864
	v_exp_f32_e32 v69, v69
	v_add_f32_e32 v239, v67, v239
	v_exp_f32_e32 v70, v70
	v_add_f32_e32 v238, v68, v238
	v_mfma_f32_32x32x16_bf16 v[32:47], v[108:111], v[156:159], v[32:47]
	ds_read_b128 v[108:111], v169 offset:40960
	v_exp_f32_e32 v71, v71
	v_add_f32_e32 v239, v69, v239
	v_cvt_pk_bf16_f32 v64, v64, v65
	v_add_f32_e32 v238, v70, v238
	v_mfma_f32_32x32x16_bf16 v[48:63], v[132:135], v[180:183], v[48:63]
	v_cvt_pk_bf16_f32 v65, v66, v67
	v_add_f32_e32 v239, v71, v239
	v_cvt_pk_bf16_f32 v66, v68, v69
	v_cvt_pk_bf16_f32 v67, v70, v71
	v_mfma_f32_32x32x16_bf16 v[32:47], v[132:135], v[180:183], v[32:47]
	v_exp_f32_e32 v72, v72
	v_exp_f32_e32 v73, v73
	v_exp_f32_e32 v74, v74
	v_add_f32_e32 v238, v72, v238
	s_waitcnt lgkmcnt(4)
	v_mfma_f32_32x32x16_bf16 v[16:31], v[112:115], v[80:83], v[16:31]
	ds_read_b128 v[112:115], v162 offset:13312
	v_exp_f32_e32 v75, v75
	v_add_f32_e32 v239, v73, v239
	v_exp_f32_e32 v76, v76
	v_add_f32_e32 v238, v74, v238
	v_mfma_f32_32x32x16_bf16 v[0:15], v[116:119], v[80:83], v[0:15]
	ds_read_b128 v[116:119], v162 offset:17408
	v_exp_f32_e32 v77, v77
	v_add_f32_e32 v239, v75, v239
	v_exp_f32_e32 v78, v78
	v_add_f32_e32 v238, v76, v238
	v_mfma_f32_32x32x16_bf16 v[16:31], v[120:123], v[88:91], v[16:31]
	ds_read_b128 v[120:123], v163 offset:13312
	v_exp_f32_e32 v79, v79
	v_add_f32_e32 v239, v77, v239
	v_cvt_pk_bf16_f32 v72, v72, v73
	v_add_f32_e32 v238, v78, v238
	v_mfma_f32_32x32x16_bf16 v[0:15], v[124:127], v[88:91], v[0:15]
	ds_read_b128 v[124:127], v163 offset:17408
	v_cvt_pk_bf16_f32 v73, v74, v75
	v_add_f32_e32 v239, v79, v239
	v_cvt_pk_bf16_f32 v74, v76, v77
	v_cvt_pk_bf16_f32 v75, v78, v79
	s_waitcnt lgkmcnt(4)
	v_mfma_f32_32x32x16_bf16 v[16:31], v[96:99], v[64:67], v[16:31]
	ds_read_b128 v[96:99], v160 offset:13312
	v_max3_f32 v240, v48, v32, v49
	v_max3_f32 v241, v33, v50, v34
	v_max3_f32 v240, v51, v35, v240
	v_max3_f32 v241, v52, v36, v241
	v_mfma_f32_32x32x16_bf16 v[0:15], v[100:103], v[64:67], v[0:15]
	ds_read_b128 v[100:103], v160 offset:17408
	v_max3_f32 v240, v53, v37, v240
	v_max3_f32 v241, v54, v38, v241
	v_max3_f32 v240, v55, v39, v240
	v_max3_f32 v241, v56, v40, v241
	v_mfma_f32_32x32x16_bf16 v[16:31], v[104:107], v[72:75], v[16:31]
	ds_read_b128 v[104:107], v161 offset:13312
	v_max3_f32 v240, v57, v41, v240
	v_max3_f32 v241, v58, v42, v241
	v_max3_f32 v240, v59, v43, v240
	v_max3_f32 v241, v60, v44, v241
	v_mfma_f32_32x32x16_bf16 v[0:15], v[108:111], v[72:75], v[0:15]
	ds_read_b128 v[108:111], v161 offset:17408
	v_max3_f32 v240, v61, v45, v240
	v_max3_f32 v241, v62, v46, v241
	v_max3_f32 v240, v63, v47, v240
	v_max_f32_e32 v240, v240, v241
	v_lshl_add_u64 v[130:131], v[130:131], 0, s[84:85]
	v_lshl_add_u64 v[220:221], v[220:221], 0, s[84:85]
	s_mov_b32 s0, s31
	s_add_i32 s31, s31, 2
	s_cmp_lt_u32 s0, s19
	s_cbranch_scc1 .LBB0_268
	s_branch .Lm_fold
